# ph0: non-temporal (nt) policy on the once-read f32 weight loads (mod GEMV, transpose items); on top of v44
# speedup vs baseline: 1.0041x; 1.0041x over previous
.LBB0_35:
	s_lshl_b32 s7, s4, 1
	s_lshl_b32 s6, s3, 1
	v_or_b32_e32 v75, s7, v54
	s_add_i32 s27, s7, 4
	v_or_b32_e32 v73, s6, v17
	s_add_i32 s26, s6, 4
	s_add_i32 s72, s7, 8
	v_add_lshl_u32 v18, v75, s1, 11
	v_or_b32_e32 v79, s27, v54
	v_mov_b32_e32 v3, v19
	s_add_i32 s74, s7, 12
	v_add_lshl_u32 v2, v73, s2, 11
	v_or_b32_e32 v77, s26, v17
	v_or_b32_e32 v114, s72, v54
	v_lshl_add_u64 v[90:91], v[18:19], 2, v[0:1]
	v_add_lshl_u32 v18, v79, s1, 11
	v_mov_b32_e32 v5, v19
	s_add_i32 s71, s6, 8
	s_add_i32 s73, s6, 12
	s_add_i32 s76, s7, 16
	v_or_b32_e32 v116, s74, v54
	v_lshl_add_u64 v[2:3], v[2:3], 2, v[0:1]
	v_add_lshl_u32 v4, v77, s2, 11
	v_lshl_add_u64 v[112:113], v[18:19], 2, v[0:1]
	v_add_lshl_u32 v18, v114, s1, 11
	s_add_i32 s78, s7, 20
	v_or_b32_e32 v111, s71, v17
	v_or_b32_e32 v115, s73, v17
	v_or_b32_e32 v118, s76, v54
	v_lshl_add_u64 v[4:5], v[4:5], 2, v[0:1]
	global_load_dword v126, v[90:91], off nt
	global_load_dword v127, v[2:3], off nt
	global_load_dword v128, v[112:113], off nt
	global_load_dword v129, v[4:5], off nt
	v_lshl_add_u64 v[2:3], v[18:19], 2, v[0:1]
	v_add_lshl_u32 v18, v116, s1, 11
	v_mov_b32_e32 v7, v19
	v_mov_b32_e32 v9, v19
	s_add_i32 s75, s6, 16
	s_add_i32 s77, s6, 20
	s_add_i32 s80, s7, 24
	v_or_b32_e32 v120, s78, v54
	v_add_lshl_u32 v6, v111, s2, 11
	v_add_lshl_u32 v8, v115, s2, 11
	v_lshl_add_u64 v[4:5], v[18:19], 2, v[0:1]
	v_add_lshl_u32 v18, v118, s1, 11
	s_add_i32 s79, s6, 24
	s_add_i32 s6, s6, 28
	s_add_i32 s7, s7, 28
	v_or_b32_e32 v117, s75, v17
	v_or_b32_e32 v119, s77, v17
	v_or_b32_e32 v122, s80, v54
	v_lshl_add_u64 v[6:7], v[6:7], 2, v[0:1]
	v_lshl_add_u64 v[8:9], v[8:9], 2, v[0:1]
	global_load_dword v130, v[2:3], off nt
	global_load_dword v131, v[6:7], off nt
	global_load_dword v132, v[4:5], off nt
	global_load_dword v133, v[8:9], off nt
	v_lshl_add_u64 v[2:3], v[18:19], 2, v[0:1]
	v_add_lshl_u32 v18, v120, s1, 11
	v_mov_b32_e32 v11, v19
	v_mov_b32_e32 v13, v19
	v_or_b32_e32 v121, s79, v17
	v_or_b32_e32 v124, s6, v17
	v_or_b32_e32 v123, s7, v54
	v_add_lshl_u32 v10, v117, s2, 11
	v_add_lshl_u32 v12, v119, s2, 11
	v_lshl_add_u64 v[4:5], v[18:19], 2, v[0:1]
	v_add_lshl_u32 v18, v122, s1, 11
	v_mov_b32_e32 v15, v19
	v_mov_b32_e32 v89, v19
	v_add_lshl_u32 v14, v121, s2, 11
	v_add_lshl_u32 v88, v124, s2, 11
	v_lshl_add_u64 v[10:11], v[10:11], 2, v[0:1]
	v_lshl_add_u64 v[12:13], v[12:13], 2, v[0:1]
	global_load_dword v134, v[2:3], off nt
	global_load_dword v135, v[10:11], off nt
	global_load_dword v136, v[4:5], off nt
	global_load_dword v137, v[12:13], off nt
	v_lshl_add_u64 v[2:3], v[18:19], 2, v[0:1]
	v_add_lshl_u32 v18, v123, s1, 11
	v_lshl_add_u64 v[14:15], v[14:15], 2, v[0:1]
	v_lshl_add_u64 v[88:89], v[88:89], 2, v[0:1]
	v_lshl_add_u64 v[4:5], v[18:19], 2, v[0:1]
	global_load_dword v18, v[2:3], off nt
	global_load_dword v138, v[14:15], off nt
	global_load_dword v139, v[4:5], off nt
	global_load_dword v140, v[88:89], off nt
	s_add_i32 s4, s4, 16
	s_add_i32 s3, s3, 16
	s_add_i32 s5, s5, -16
	v_mad_u64_u32 v[2:3], s[6:7], v75, s49, v[56:57]
	s_cmp_lg_u32 s5, 0
	v_mad_u64_u32 v[4:5], s[6:7], v73, s49, v[56:57]
	v_mad_u64_u32 v[6:7], s[6:7], v79, s49, v[56:57]
	v_mad_u64_u32 v[8:9], s[6:7], v77, s49, v[56:57]
	v_mad_u64_u32 v[10:11], s[6:7], v114, s49, v[56:57]
	v_mad_u64_u32 v[12:13], s[6:7], v111, s49, v[56:57]
	v_mad_u64_u32 v[14:15], s[6:7], v116, s49, v[56:57]
	v_mad_u64_u32 v[88:89], s[6:7], v115, s49, v[56:57]
	v_mad_u64_u32 v[90:91], s[6:7], v118, s49, v[56:57]
	v_mad_u64_u32 v[112:113], s[6:7], v117, s49, v[56:57]
	v_mad_u64_u32 v[114:115], s[6:7], v120, s49, v[56:57]
	v_mad_u64_u32 v[116:117], s[6:7], v119, s49, v[56:57]
	v_mad_u64_u32 v[118:119], s[6:7], v122, s49, v[56:57]
	v_mad_u64_u32 v[120:121], s[6:7], v121, s49, v[56:57]
	v_mad_u64_u32 v[122:123], s[6:7], v123, s49, v[56:57]
	v_mad_u64_u32 v[124:125], s[6:7], v124, s49, v[56:57]
	s_waitcnt vmcnt(0)
	ds_write_b32 v2, v126
	ds_write_b32 v4, v127
	ds_write_b32 v6, v128
	ds_write_b32 v8, v129
	ds_write_b32 v10, v130
	ds_write_b32 v12, v131
	ds_write_b32 v14, v132
	ds_write_b32 v88, v133
	ds_write_b32 v90, v134
	ds_write_b32 v112, v135
	ds_write_b32 v114, v136
	ds_write_b32 v116, v137
	ds_write_b32 v118, v18
	ds_write_b32 v120, v138
	ds_write_b32 v122, v139
	ds_write_b32 v124, v140
	s_cbranch_scc1 .LBB0_35
	s_waitcnt lgkmcnt(0)
	ds_read2_b32 v[4:5], v94 offset1:8
	ds_read2_b32 v[8:9], v94 offset0:33 offset1:41
	ds_read2_b32 v[10:11], v94 offset0:66 offset1:74
	ds_read2_b32 v[12:13], v94 offset0:99 offset1:107
	ds_read2_b32 v[14:15], v94 offset0:132 offset1:140
	s_waitcnt lgkmcnt(0)
	v_bfe_u32 v0, v4, 16, 1
	v_add3_u32 v0, v4, v0, s65
	v_bfe_u32 v1, v8, 16, 1
	v_lshrrev_b32_e32 v0, 16, v0
	v_add3_u32 v1, v8, v1, s65
	ds_read2_b32 v[88:89], v94 offset0:165 offset1:173
	v_and_or_b32 v0, v1, s66, v0
	v_bfe_u32 v1, v10, 16, 1
	v_add3_u32 v1, v10, v1, s65
	v_bfe_u32 v2, v12, 16, 1
	ds_read2_b32 v[90:91], v94 offset0:198 offset1:206
	v_lshrrev_b32_e32 v1, 16, v1
	v_add3_u32 v2, v12, v2, s65
	ds_read2_b32 v[112:113], v94 offset0:231 offset1:239
	v_and_or_b32 v1, v2, s66, v1
	v_bfe_u32 v2, v14, 16, 1
	v_add3_u32 v2, v14, v2, s65
	s_waitcnt lgkmcnt(2)
	v_bfe_u32 v3, v88, 16, 1
	s_lshl_b64 s[2:3], s[24:25], 23
	v_lshrrev_b32_e32 v2, 16, v2
	v_add3_u32 v3, v88, v3, s65
	s_add_u32 s2, s36, s2
	v_and_or_b32 v2, v3, s66, v2
	s_waitcnt lgkmcnt(1)
	v_bfe_u32 v3, v90, 16, 1
	s_addc_u32 s3, s37, s3
	s_lshl_b32 s1, s1, 1
	v_add3_u32 v3, v90, v3, s65
	s_waitcnt lgkmcnt(0)
	v_bfe_u32 v4, v112, 16, 1
	s_add_u32 s2, s2, s1
	v_lshrrev_b32_e32 v3, 16, v3
	v_add3_u32 v4, v112, v4, s65
	s_addc_u32 s3, s3, 0
	v_lshlrev_b32_e32 v18, 1, v24
	v_and_or_b32 v3, v4, s66, v3
	v_or_b32_e32 v4, s0, v25
	v_lshl_add_u64 v[6:7], s[2:3], 0, v[18:19]
	v_lshlrev_b32_e32 v18, 12, v4
	v_lshl_add_u64 v[114:115], v[6:7], 0, v[18:19]
	global_store_dwordx4 v[114:115], v[0:3], off
	v_bfe_u32 v4, v113, 16, 1
	v_or_b32_e32 v8, s0, v33
	v_bfe_u32 v0, v5, 16, 1
	v_add3_u32 v0, v5, v0, s65
	v_bfe_u32 v1, v9, 16, 1
	v_lshrrev_b32_e32 v0, 16, v0
	v_add3_u32 v1, v9, v1, s65
	v_and_or_b32 v0, v1, s66, v0
	v_bfe_u32 v1, v11, 16, 1
	v_add3_u32 v1, v11, v1, s65
	v_bfe_u32 v2, v13, 16, 1
	v_lshrrev_b32_e32 v1, 16, v1
	v_add3_u32 v2, v13, v2, s65
	v_and_or_b32 v1, v2, s66, v1
	v_bfe_u32 v2, v15, 16, 1
	v_add3_u32 v2, v15, v2, s65
	v_bfe_u32 v3, v89, 16, 1
	v_lshrrev_b32_e32 v2, 16, v2
	v_add3_u32 v3, v89, v3, s65
	v_and_or_b32 v2, v3, s66, v2
	v_bfe_u32 v3, v91, 16, 1
	v_add3_u32 v3, v91, v3, s65
	v_lshrrev_b32_e32 v3, 16, v3
	v_add3_u32 v4, v113, v4, s65
	v_lshlrev_b32_e32 v18, 12, v8
	v_and_or_b32 v3, v4, s66, v3
	ds_read2_b32 v[4:5], v94 offset0:16 offset1:24
	v_lshl_add_u64 v[8:9], v[6:7], 0, v[18:19]
	global_store_dwordx4 v[8:9], v[0:3], off
	ds_read2_b32 v[8:9], v94 offset0:49 offset1:57
	ds_read2_b32 v[10:11], v94 offset0:82 offset1:90
	ds_read2_b32 v[12:13], v94 offset0:115 offset1:123
	s_waitcnt lgkmcnt(3)
	v_bfe_u32 v0, v4, 16, 1
	v_add3_u32 v0, v4, v0, s65
	s_waitcnt lgkmcnt(2)
	v_bfe_u32 v1, v8, 16, 1
	ds_read2_b32 v[14:15], v94 offset0:148 offset1:156
	v_lshrrev_b32_e32 v0, 16, v0
	v_add3_u32 v1, v8, v1, s65
	ds_read2_b32 v[88:89], v94 offset0:181 offset1:189
	v_and_or_b32 v0, v1, s66, v0
	s_waitcnt lgkmcnt(3)
	v_bfe_u32 v1, v10, 16, 1
	v_add3_u32 v1, v10, v1, s65
	s_waitcnt lgkmcnt(2)
	v_bfe_u32 v2, v12, 16, 1
	ds_read2_b32 v[90:91], v94 offset0:214 offset1:222
	v_lshrrev_b32_e32 v1, 16, v1
	v_add3_u32 v2, v12, v2, s65
	ds_read2_b32 v[112:113], v94 offset0:247 offset1:255
	v_and_or_b32 v1, v2, s66, v1
	s_waitcnt lgkmcnt(3)
	v_bfe_u32 v2, v14, 16, 1
	v_add3_u32 v2, v14, v2, s65
	s_waitcnt lgkmcnt(2)
	v_bfe_u32 v3, v88, 16, 1
	v_lshrrev_b32_e32 v2, 16, v2
	v_add3_u32 v3, v88, v3, s65
	v_and_or_b32 v2, v3, s66, v2
	s_waitcnt lgkmcnt(1)
	v_bfe_u32 v3, v90, 16, 1
	v_add3_u32 v3, v90, v3, s65
	s_waitcnt lgkmcnt(0)
	v_bfe_u32 v4, v112, 16, 1
	v_lshrrev_b32_e32 v3, 16, v3
	v_add3_u32 v4, v112, v4, s65
	v_and_or_b32 v3, v4, s66, v3
	v_or_b32_e32 v4, s0, v55
	v_lshlrev_b32_e32 v18, 12, v4
	v_lshl_add_u64 v[114:115], v[6:7], 0, v[18:19]
	global_store_dwordx4 v[114:115], v[0:3], off
	v_bfe_u32 v4, v113, 16, 1
	v_add3_u32 v4, v113, v4, s65
	v_bfe_u32 v0, v5, 16, 1
	v_add3_u32 v0, v5, v0, s65
	v_bfe_u32 v1, v9, 16, 1
	v_lshrrev_b32_e32 v0, 16, v0
	v_add3_u32 v1, v9, v1, s65
	v_and_or_b32 v0, v1, s66, v0
	v_bfe_u32 v1, v11, 16, 1
	v_add3_u32 v1, v11, v1, s65
	v_bfe_u32 v2, v13, 16, 1
	v_lshrrev_b32_e32 v1, 16, v1
	v_add3_u32 v2, v13, v2, s65
	v_and_or_b32 v1, v2, s66, v1
	v_bfe_u32 v2, v15, 16, 1
	v_add3_u32 v2, v15, v2, s65
	v_bfe_u32 v3, v89, 16, 1
	v_lshrrev_b32_e32 v2, 16, v2
	v_add3_u32 v3, v89, v3, s65
	v_and_or_b32 v2, v3, s66, v2
	v_bfe_u32 v3, v91, 16, 1
	v_add3_u32 v3, v91, v3, s65
	v_lshrrev_b32_e32 v3, 16, v3
	v_and_or_b32 v3, v4, s66, v3
	v_or_b32_e32 v4, s0, v57
	v_lshlrev_b32_e32 v18, 12, v4
	v_lshl_add_u64 v[4:5], v[6:7], 0, v[18:19]
	global_store_dwordx4 v[4:5], v[0:3], off
	s_waitcnt lgkmcnt(0)

.LBB0_45:
	global_load_dword v120, v[8:9], off nt
	v_lshl_add_u64 v[136:137], v[6:7], 0, s[4:5]
	global_load_dword v128, v[136:137], off
	v_lshl_add_u64 v[138:139], v[4:5], 0, s[4:5]
	v_add_u32_e32 v18, 0x1800, v2
	v_lshl_add_u64 v[136:137], v[18:19], 2, v[0:1]
	global_load_dword v121, v[136:137], off nt
	global_load_dword v129, v[138:139], off offset:8
	v_add_u32_e32 v18, 0x3000, v2
	v_lshl_add_u64 v[136:137], v[18:19], 2, v[0:1]
	global_load_dword v122, v[136:137], off nt
	global_load_dword v130, v[138:139], off offset:16
	v_add_u32_e32 v18, 0x4800, v2
	v_lshl_add_u64 v[136:137], v[18:19], 2, v[0:1]
	global_load_dword v123, v[136:137], off nt
	global_load_dword v131, v[138:139], off offset:24
	v_add_u32_e32 v18, 0x6000, v2
	v_lshl_add_u64 v[136:137], v[18:19], 2, v[0:1]
	global_load_dword v124, v[136:137], off nt
	global_load_dword v132, v[138:139], off offset:32
	v_add_u32_e32 v18, 0x7800, v2
	v_lshl_add_u64 v[136:137], v[18:19], 2, v[0:1]
	global_load_dword v125, v[136:137], off nt
	global_load_dword v133, v[138:139], off offset:40
	v_add_u32_e32 v18, 0x9000, v2
	v_lshl_add_u64 v[136:137], v[18:19], 2, v[0:1]
	global_load_dword v126, v[136:137], off nt
	global_load_dword v134, v[138:139], off offset:48
	v_add_u32_e32 v18, 0xa800, v2
	v_lshl_add_u64 v[136:137], v[18:19], 2, v[0:1]
	global_load_dword v127, v[136:137], off nt
	global_load_dword v135, v[138:139], off offset:56
	s_waitcnt vmcnt(0)
	v_mul_f32_e32 v120, v120, v128
	v_mul_f32_e32 v121, v121, v129
	v_mul_f32_e32 v122, v122, v130
	v_mul_f32_e32 v123, v123, v131
	v_mul_f32_e32 v124, v124, v132
	v_mul_f32_e32 v125, v125, v133
	v_mul_f32_e32 v126, v126, v134
	v_mul_f32_e32 v127, v127, v135
	ds_write_b32 v3, v120
	ds_write_b32 v3, v121 offset:264
	ds_write_b32 v3, v122 offset:528
	ds_write_b32 v3, v123 offset:792
	ds_write_b32 v3, v124 offset:1056
	ds_write_b32 v3, v125 offset:1320
	ds_write_b32 v3, v126 offset:1584
	ds_write_b32 v3, v127 offset:1848
	s_add_u32 s4, s4, 64
	s_addc_u32 s5, s5, 0
	s_mov_b64 s[0:1], 0x30000
	v_add_u32_e32 v3, 0x840, v3
	v_add_u32_e32 v2, 0xc000, v2
	s_cmpk_lg_i32 s4, 0x100
	v_lshl_add_u64 v[8:9], v[8:9], 0, s[0:1]
	s_cbranch_scc1 .LBB0_45

.LBB0_66:
	v_lshl_add_u64 v[136:137], v[88:89], 0, s[2:3]
	global_load_dword v120, v[136:137], off nt
	v_lshl_add_u64 v[136:137], s[4:5], 0, v[18:19]
	global_load_dword v128, v[136:137], off
	v_lshl_add_u64 v[138:139], s[4:5], 0, v[0:1]
	v_lshl_add_u64 v[136:137], v[14:15], 0, s[2:3]
	global_load_dword v121, v[136:137], off nt
	global_load_dword v129, v[138:139], off offset:8
	v_lshl_add_u64 v[136:137], v[12:13], 0, s[2:3]
	global_load_dword v122, v[136:137], off nt
	global_load_dword v130, v[138:139], off offset:16
	v_lshl_add_u64 v[136:137], v[10:11], 0, s[2:3]
	global_load_dword v123, v[136:137], off nt
	global_load_dword v131, v[138:139], off offset:24
	v_lshl_add_u64 v[136:137], v[8:9], 0, s[2:3]
	global_load_dword v124, v[136:137], off nt
	global_load_dword v132, v[138:139], off offset:32
	v_lshl_add_u64 v[136:137], v[6:7], 0, s[2:3]
	global_load_dword v125, v[136:137], off nt
	global_load_dword v133, v[138:139], off offset:40
	v_lshl_add_u64 v[136:137], v[4:5], 0, s[2:3]
	global_load_dword v126, v[136:137], off nt
	global_load_dword v134, v[138:139], off offset:48
	v_lshl_add_u64 v[136:137], v[2:3], 0, s[2:3]
	global_load_dword v127, v[136:137], off nt
	global_load_dword v135, v[138:139], off offset:56
	s_waitcnt vmcnt(0)
	v_mul_f32_e32 v120, v120, v128
	v_mul_f32_e32 v121, v121, v129
	v_mul_f32_e32 v122, v122, v130
	v_mul_f32_e32 v123, v123, v131
	v_mul_f32_e32 v124, v124, v132
	v_mul_f32_e32 v125, v125, v133
	v_mul_f32_e32 v126, v126, v134
	v_mul_f32_e32 v127, v127, v135
	ds_write_b32 v73, v120
	ds_write_b32 v73, v121 offset:264
	ds_write_b32 v73, v122 offset:528
	ds_write_b32 v73, v123 offset:792
	ds_write_b32 v73, v124 offset:1056
	ds_write_b32 v73, v125 offset:1320
	ds_write_b32 v73, v126 offset:1584
	ds_write_b32 v73, v127 offset:1848
	s_add_u32 s2, s2, 0x20000
	s_addc_u32 s3, s3, 0
	s_add_u32 s4, s4, 64
	s_addc_u32 s5, s5, 0
	s_cmp_lg_u32 s2, 0x80000
	v_add_u32_e32 v73, 0x840, v73
	s_cbranch_scc1 .LBB0_66

.LBB0_86:
	s_lshl_b32 s24, s5, 1
	s_lshl_b32 s7, s4, 1
	v_or_b32_e32 v75, s24, v54
	s_add_i32 s27, s24, 4
	v_or_b32_e32 v73, s7, v17
	s_add_i32 s26, s7, 4
	s_add_i32 s72, s24, 8
	v_add_lshl_u32 v18, v75, s0, 9
	v_or_b32_e32 v79, s27, v54
	v_mov_b32_e32 v3, v19
	s_add_i32 s74, s24, 12
	v_add_lshl_u32 v2, v73, s3, 9
	v_or_b32_e32 v77, s26, v17
	v_or_b32_e32 v114, s72, v54
	v_lshl_add_u64 v[90:91], v[18:19], 2, v[0:1]
	v_add_lshl_u32 v18, v79, s0, 9
	v_mov_b32_e32 v5, v19
	s_add_i32 s71, s7, 8
	s_add_i32 s73, s7, 12
	s_add_i32 s76, s24, 16
	v_or_b32_e32 v116, s74, v54
	v_lshl_add_u64 v[2:3], v[2:3], 2, v[0:1]
	v_add_lshl_u32 v4, v77, s3, 9
	v_lshl_add_u64 v[112:113], v[18:19], 2, v[0:1]
	v_add_lshl_u32 v18, v114, s0, 9
	s_add_i32 s78, s24, 20
	v_or_b32_e32 v111, s71, v17
	v_or_b32_e32 v115, s73, v17
	v_or_b32_e32 v118, s76, v54
	v_lshl_add_u64 v[4:5], v[4:5], 2, v[0:1]
	global_load_dword v126, v[90:91], off nt
	global_load_dword v127, v[2:3], off nt
	global_load_dword v128, v[112:113], off nt
	global_load_dword v129, v[4:5], off nt
	v_lshl_add_u64 v[2:3], v[18:19], 2, v[0:1]
	v_add_lshl_u32 v18, v116, s0, 9
	v_mov_b32_e32 v7, v19
	v_mov_b32_e32 v9, v19
	s_add_i32 s75, s7, 16
	s_add_i32 s77, s7, 20
	s_add_i32 s80, s24, 24
	v_or_b32_e32 v120, s78, v54
	v_add_lshl_u32 v6, v111, s3, 9
	v_add_lshl_u32 v8, v115, s3, 9
	v_lshl_add_u64 v[4:5], v[18:19], 2, v[0:1]
	v_add_lshl_u32 v18, v118, s0, 9
	s_add_i32 s79, s7, 24
	s_add_i32 s7, s7, 28
	s_add_i32 s24, s24, 28
	v_or_b32_e32 v117, s75, v17
	v_or_b32_e32 v119, s77, v17
	v_or_b32_e32 v122, s80, v54
	v_lshl_add_u64 v[6:7], v[6:7], 2, v[0:1]
	v_lshl_add_u64 v[8:9], v[8:9], 2, v[0:1]
	global_load_dword v130, v[2:3], off nt
	global_load_dword v131, v[6:7], off nt
	global_load_dword v132, v[4:5], off nt
	global_load_dword v133, v[8:9], off nt
	v_lshl_add_u64 v[2:3], v[18:19], 2, v[0:1]
	v_add_lshl_u32 v18, v120, s0, 9
	v_mov_b32_e32 v11, v19
	v_mov_b32_e32 v13, v19
	v_or_b32_e32 v121, s79, v17
	v_or_b32_e32 v124, s7, v17
	v_or_b32_e32 v123, s24, v54
	v_add_lshl_u32 v10, v117, s3, 9
	v_add_lshl_u32 v12, v119, s3, 9
	v_lshl_add_u64 v[4:5], v[18:19], 2, v[0:1]
	v_add_lshl_u32 v18, v122, s0, 9
	v_mov_b32_e32 v15, v19
	v_mov_b32_e32 v89, v19
	v_add_lshl_u32 v14, v121, s3, 9
	v_add_lshl_u32 v88, v124, s3, 9
	v_lshl_add_u64 v[10:11], v[10:11], 2, v[0:1]
	v_lshl_add_u64 v[12:13], v[12:13], 2, v[0:1]
	global_load_dword v134, v[2:3], off nt
	global_load_dword v135, v[10:11], off nt
	global_load_dword v136, v[4:5], off nt
	global_load_dword v137, v[12:13], off nt
	v_lshl_add_u64 v[2:3], v[18:19], 2, v[0:1]
	v_add_lshl_u32 v18, v123, s0, 9
	v_lshl_add_u64 v[14:15], v[14:15], 2, v[0:1]
	v_lshl_add_u64 v[88:89], v[88:89], 2, v[0:1]
	v_lshl_add_u64 v[4:5], v[18:19], 2, v[0:1]
	global_load_dword v18, v[2:3], off nt
	global_load_dword v138, v[14:15], off nt
	global_load_dword v139, v[4:5], off nt
	global_load_dword v140, v[88:89], off nt
	s_add_i32 s5, s5, 16
	s_add_i32 s4, s4, 16
	s_add_i32 s6, s6, -16
	v_mad_u64_u32 v[2:3], s[26:27], v75, s49, v[56:57]
	s_cmp_lg_u32 s6, 0
	v_mad_u64_u32 v[4:5], s[26:27], v73, s49, v[56:57]
	v_mad_u64_u32 v[6:7], s[26:27], v79, s49, v[56:57]
	v_mad_u64_u32 v[8:9], s[26:27], v77, s49, v[56:57]
	v_mad_u64_u32 v[10:11], s[26:27], v114, s49, v[56:57]
	v_mad_u64_u32 v[12:13], s[26:27], v111, s49, v[56:57]
	v_mad_u64_u32 v[14:15], s[26:27], v116, s49, v[56:57]
	v_mad_u64_u32 v[88:89], s[26:27], v115, s49, v[56:57]
	v_mad_u64_u32 v[90:91], s[26:27], v118, s49, v[56:57]
	v_mad_u64_u32 v[112:113], s[26:27], v117, s49, v[56:57]
	v_mad_u64_u32 v[114:115], s[26:27], v120, s49, v[56:57]
	v_mad_u64_u32 v[116:117], s[26:27], v119, s49, v[56:57]
	v_mad_u64_u32 v[118:119], s[26:27], v122, s49, v[56:57]
	v_mad_u64_u32 v[120:121], s[26:27], v121, s49, v[56:57]
	v_mad_u64_u32 v[122:123], s[26:27], v123, s49, v[56:57]
	v_mad_u64_u32 v[124:125], s[26:27], v124, s49, v[56:57]
	s_waitcnt vmcnt(0)
	ds_write_b32 v2, v126
	ds_write_b32 v4, v127
	ds_write_b32 v6, v128
	ds_write_b32 v8, v129
	ds_write_b32 v10, v130
	ds_write_b32 v12, v131
	ds_write_b32 v14, v132
	ds_write_b32 v88, v133
	ds_write_b32 v90, v134
	ds_write_b32 v112, v135
	ds_write_b32 v114, v136
	ds_write_b32 v116, v137
	ds_write_b32 v118, v18
	ds_write_b32 v120, v138
	ds_write_b32 v122, v139
	ds_write_b32 v124, v140
	s_cbranch_scc1 .LBB0_86
	s_waitcnt lgkmcnt(0)
	ds_read2_b32 v[4:5], v94 offset1:8
	ds_read2_b32 v[8:9], v94 offset0:33 offset1:41
	ds_read2_b32 v[10:11], v94 offset0:66 offset1:74
	ds_read2_b32 v[12:13], v94 offset0:99 offset1:107
	ds_read2_b32 v[14:15], v94 offset0:132 offset1:140
	s_waitcnt lgkmcnt(0)
	v_bfe_u32 v0, v4, 16, 1
	v_add3_u32 v0, v4, v0, s65
	v_bfe_u32 v1, v8, 16, 1
	v_lshrrev_b32_e32 v0, 16, v0
	v_add3_u32 v1, v8, v1, s65
	ds_read2_b32 v[88:89], v94 offset0:165 offset1:173
	v_and_or_b32 v0, v1, s66, v0
	v_bfe_u32 v1, v10, 16, 1
	v_add3_u32 v1, v10, v1, s65
	v_bfe_u32 v2, v12, 16, 1
	ds_read2_b32 v[90:91], v94 offset0:198 offset1:206
	s_cmpk_lt_u32 s1, 0x200
	v_lshrrev_b32_e32 v1, 16, v1
	v_add3_u32 v2, v12, v2, s65
	ds_read2_b32 v[112:113], v94 offset0:231 offset1:239
	s_cselect_b64 s[4:5], -1, 0
	v_and_or_b32 v1, v2, s66, v1
	v_bfe_u32 v2, v14, 16, 1
	s_and_b64 s[4:5], s[4:5], exec
	s_mov_b32 s1, 0x11600000
	v_add3_u32 v2, v14, v2, s65
	s_waitcnt lgkmcnt(2)
	v_bfe_u32 v3, v88, 16, 1
	s_cselect_b32 s1, s1, 0x11b00000
	v_lshrrev_b32_e32 v2, 16, v2
	v_add3_u32 v3, v88, v3, s65
	s_cselect_b32 s3, 0x300, 0
	s_add_u32 s1, s28, s1
	v_and_or_b32 v2, v3, s66, v2
	s_waitcnt lgkmcnt(1)
	v_bfe_u32 v3, v90, 16, 1
	s_addc_u32 s4, s29, 0
	s_add_i32 s3, s3, s2
	s_lshl_b32 s0, s0, 1
	v_add3_u32 v3, v90, v3, s65
	s_waitcnt lgkmcnt(0)
	v_bfe_u32 v4, v112, 16, 1
	s_add_u32 s0, s1, s0
	v_lshrrev_b32_e32 v3, 16, v3
	v_add3_u32 v4, v112, v4, s65
	s_addc_u32 s1, s4, 0
	v_lshlrev_b32_e32 v18, 1, v24
	v_and_or_b32 v3, v4, s66, v3
	v_or_b32_e32 v4, s3, v25
	v_lshl_add_u64 v[6:7], s[0:1], 0, v[18:19]
	v_lshlrev_b32_e32 v18, 12, v4
	v_lshl_add_u64 v[114:115], v[6:7], 0, v[18:19]
	global_store_dwordx4 v[114:115], v[0:3], off
	v_bfe_u32 v4, v113, 16, 1
	v_or_b32_e32 v8, s3, v33
	v_bfe_u32 v0, v5, 16, 1
	v_add3_u32 v0, v5, v0, s65
	v_bfe_u32 v1, v9, 16, 1
	v_lshrrev_b32_e32 v0, 16, v0
	v_add3_u32 v1, v9, v1, s65
	v_and_or_b32 v0, v1, s66, v0
	v_bfe_u32 v1, v11, 16, 1
	v_add3_u32 v1, v11, v1, s65
	v_bfe_u32 v2, v13, 16, 1
	v_lshrrev_b32_e32 v1, 16, v1
	v_add3_u32 v2, v13, v2, s65
	v_and_or_b32 v1, v2, s66, v1
	v_bfe_u32 v2, v15, 16, 1
	v_add3_u32 v2, v15, v2, s65
	v_bfe_u32 v3, v89, 16, 1
	v_lshrrev_b32_e32 v2, 16, v2
	v_add3_u32 v3, v89, v3, s65
	v_and_or_b32 v2, v3, s66, v2
	v_bfe_u32 v3, v91, 16, 1
	v_add3_u32 v3, v91, v3, s65
	v_lshrrev_b32_e32 v3, 16, v3
	v_add3_u32 v4, v113, v4, s65
	v_lshlrev_b32_e32 v18, 12, v8
	v_and_or_b32 v3, v4, s66, v3
	ds_read2_b32 v[4:5], v94 offset0:16 offset1:24
	v_lshl_add_u64 v[8:9], v[6:7], 0, v[18:19]
	global_store_dwordx4 v[8:9], v[0:3], off
	ds_read2_b32 v[8:9], v94 offset0:49 offset1:57
	ds_read2_b32 v[10:11], v94 offset0:82 offset1:90
	ds_read2_b32 v[12:13], v94 offset0:115 offset1:123
	s_waitcnt lgkmcnt(3)
	v_bfe_u32 v0, v4, 16, 1
	v_add3_u32 v0, v4, v0, s65
	s_waitcnt lgkmcnt(2)
	v_bfe_u32 v1, v8, 16, 1
	ds_read2_b32 v[14:15], v94 offset0:148 offset1:156
	v_lshrrev_b32_e32 v0, 16, v0
	v_add3_u32 v1, v8, v1, s65
	ds_read2_b32 v[88:89], v94 offset0:181 offset1:189
	v_and_or_b32 v0, v1, s66, v0
	s_waitcnt lgkmcnt(3)
	v_bfe_u32 v1, v10, 16, 1
	v_add3_u32 v1, v10, v1, s65
	s_waitcnt lgkmcnt(2)
	v_bfe_u32 v2, v12, 16, 1
	ds_read2_b32 v[90:91], v94 offset0:214 offset1:222
	v_lshrrev_b32_e32 v1, 16, v1
	v_add3_u32 v2, v12, v2, s65
	ds_read2_b32 v[112:113], v94 offset0:247 offset1:255
	v_and_or_b32 v1, v2, s66, v1
	s_waitcnt lgkmcnt(3)
	v_bfe_u32 v2, v14, 16, 1
	v_add3_u32 v2, v14, v2, s65
	s_waitcnt lgkmcnt(2)
	v_bfe_u32 v3, v88, 16, 1
	v_lshrrev_b32_e32 v2, 16, v2
	v_add3_u32 v3, v88, v3, s65
	v_and_or_b32 v2, v3, s66, v2
	s_waitcnt lgkmcnt(1)
	v_bfe_u32 v3, v90, 16, 1
	v_add3_u32 v3, v90, v3, s65
	s_waitcnt lgkmcnt(0)
	v_bfe_u32 v4, v112, 16, 1
	v_lshrrev_b32_e32 v3, 16, v3
	v_add3_u32 v4, v112, v4, s65
	v_and_or_b32 v3, v4, s66, v3
	v_or_b32_e32 v4, s3, v55
	v_lshlrev_b32_e32 v18, 12, v4
	v_lshl_add_u64 v[114:115], v[6:7], 0, v[18:19]
	global_store_dwordx4 v[114:115], v[0:3], off
	v_bfe_u32 v4, v113, 16, 1
	v_add3_u32 v4, v113, v4, s65
	v_bfe_u32 v0, v5, 16, 1
	v_add3_u32 v0, v5, v0, s65
	v_bfe_u32 v1, v9, 16, 1
	v_lshrrev_b32_e32 v0, 16, v0
	v_add3_u32 v1, v9, v1, s65
	v_and_or_b32 v0, v1, s66, v0
	v_bfe_u32 v1, v11, 16, 1
	v_add3_u32 v1, v11, v1, s65
	v_bfe_u32 v2, v13, 16, 1
	v_lshrrev_b32_e32 v1, 16, v1
	v_add3_u32 v2, v13, v2, s65
	v_and_or_b32 v1, v2, s66, v1
	v_bfe_u32 v2, v15, 16, 1
	v_add3_u32 v2, v15, v2, s65
	v_bfe_u32 v3, v89, 16, 1
	v_lshrrev_b32_e32 v2, 16, v2
	v_add3_u32 v3, v89, v3, s65
	v_and_or_b32 v2, v3, s66, v2
	v_bfe_u32 v3, v91, 16, 1
	v_add3_u32 v3, v91, v3, s65
	v_lshrrev_b32_e32 v3, 16, v3
	v_and_or_b32 v3, v4, s66, v3
	v_or_b32_e32 v4, s3, v57
	v_lshlrev_b32_e32 v18, 12, v4
	v_lshl_add_u64 v[4:5], v[6:7], 0, v[18:19]
	global_store_dwordx4 v[4:5], v[0:3], off
	s_waitcnt lgkmcnt(0)

.LBB0_91:
	s_lshl_b32 s6, s3, 1
	s_lshl_b32 s5, s2, 1
	v_or_b32_e32 v75, s6, v54
	s_add_i32 s24, s6, 4
	v_or_b32_e32 v73, s5, v17
	s_add_i32 s7, s5, 4
	s_add_i32 s27, s6, 8
	v_add_lshl_u32 v18, v75, s0, 6
	v_or_b32_e32 v79, s24, v54
	v_mov_b32_e32 v1, v19
	s_add_i32 s72, s6, 12
	v_add_lshl_u32 v0, v73, s1, 6
	v_or_b32_e32 v77, s7, v17
	v_or_b32_e32 v112, s27, v54
	v_lshl_add_u64 v[88:89], v[18:19], 2, v[30:31]
	v_add_lshl_u32 v18, v79, s0, 6
	v_mov_b32_e32 v3, v19
	s_add_i32 s26, s5, 8
	s_add_i32 s71, s5, 12
	s_add_i32 s74, s6, 16
	v_or_b32_e32 v114, s72, v54
	v_lshl_add_u64 v[0:1], v[0:1], 2, v[30:31]
	v_add_lshl_u32 v2, v77, s1, 6
	v_lshl_add_u64 v[90:91], v[18:19], 2, v[30:31]
	v_add_lshl_u32 v18, v112, s0, 6
	s_add_i32 s76, s6, 20
	v_or_b32_e32 v111, s26, v17
	v_or_b32_e32 v113, s71, v17
	v_or_b32_e32 v116, s74, v54
	v_lshl_add_u64 v[2:3], v[2:3], 2, v[30:31]
	global_load_dword v124, v[88:89], off nt
	global_load_dword v125, v[0:1], off nt
	global_load_dword v126, v[90:91], off nt
	global_load_dword v127, v[2:3], off nt
	v_lshl_add_u64 v[0:1], v[18:19], 2, v[30:31]
	v_add_lshl_u32 v18, v114, s0, 6
	v_mov_b32_e32 v5, v19
	v_mov_b32_e32 v7, v19
	s_add_i32 s73, s5, 16
	s_add_i32 s75, s5, 20
	s_add_i32 s78, s6, 24
	v_or_b32_e32 v118, s76, v54
	v_add_lshl_u32 v4, v111, s1, 6
	v_add_lshl_u32 v6, v113, s1, 6
	v_lshl_add_u64 v[2:3], v[18:19], 2, v[30:31]
	v_add_lshl_u32 v18, v116, s0, 6
	s_add_i32 s77, s5, 24
	s_add_i32 s5, s5, 28
	s_add_i32 s6, s6, 28
	v_or_b32_e32 v115, s73, v17
	v_or_b32_e32 v117, s75, v17
	v_or_b32_e32 v120, s78, v54
	v_lshl_add_u64 v[4:5], v[4:5], 2, v[30:31]
	v_lshl_add_u64 v[6:7], v[6:7], 2, v[30:31]
	global_load_dword v128, v[0:1], off nt
	global_load_dword v129, v[4:5], off nt
	global_load_dword v130, v[2:3], off nt
	global_load_dword v131, v[6:7], off nt
	v_lshl_add_u64 v[0:1], v[18:19], 2, v[30:31]
	v_add_lshl_u32 v18, v118, s0, 6
	v_mov_b32_e32 v9, v19
	v_mov_b32_e32 v11, v19
	v_or_b32_e32 v119, s77, v17
	v_or_b32_e32 v122, s5, v17
	v_or_b32_e32 v121, s6, v54
	v_add_lshl_u32 v8, v115, s1, 6
	v_add_lshl_u32 v10, v117, s1, 6
	v_lshl_add_u64 v[2:3], v[18:19], 2, v[30:31]
	v_add_lshl_u32 v18, v120, s0, 6
	v_mov_b32_e32 v13, v19
	v_mov_b32_e32 v15, v19
	v_add_lshl_u32 v12, v119, s1, 6
	v_add_lshl_u32 v14, v122, s1, 6
	v_lshl_add_u64 v[8:9], v[8:9], 2, v[30:31]
	v_lshl_add_u64 v[10:11], v[10:11], 2, v[30:31]
	global_load_dword v132, v[0:1], off nt
	global_load_dword v133, v[8:9], off nt
	global_load_dword v134, v[2:3], off nt
	global_load_dword v135, v[10:11], off nt
	v_lshl_add_u64 v[0:1], v[18:19], 2, v[30:31]
	v_add_lshl_u32 v18, v121, s0, 6
	v_lshl_add_u64 v[12:13], v[12:13], 2, v[30:31]
	v_lshl_add_u64 v[14:15], v[14:15], 2, v[30:31]
	v_lshl_add_u64 v[2:3], v[18:19], 2, v[30:31]
	global_load_dword v18, v[0:1], off nt
	global_load_dword v136, v[12:13], off nt
	global_load_dword v137, v[2:3], off nt
	global_load_dword v138, v[14:15], off nt
	s_add_i32 s3, s3, 16
	s_add_i32 s2, s2, 16
	s_add_i32 s4, s4, -16
	v_mad_u64_u32 v[0:1], s[6:7], v75, s49, v[56:57]
	s_cmp_lg_u32 s4, 0
	v_mad_u64_u32 v[2:3], s[6:7], v73, s49, v[56:57]
	v_mad_u64_u32 v[4:5], s[6:7], v79, s49, v[56:57]
	v_mad_u64_u32 v[6:7], s[6:7], v77, s49, v[56:57]
	v_mad_u64_u32 v[8:9], s[6:7], v112, s49, v[56:57]
	v_mad_u64_u32 v[10:11], s[6:7], v111, s49, v[56:57]
	v_mad_u64_u32 v[12:13], s[6:7], v114, s49, v[56:57]
	v_mad_u64_u32 v[14:15], s[6:7], v113, s49, v[56:57]
	v_mad_u64_u32 v[88:89], s[6:7], v116, s49, v[56:57]
	v_mad_u64_u32 v[90:91], s[6:7], v115, s49, v[56:57]
	v_mad_u64_u32 v[112:113], s[6:7], v118, s49, v[56:57]
	v_mad_u64_u32 v[114:115], s[6:7], v117, s49, v[56:57]
	v_mad_u64_u32 v[116:117], s[6:7], v120, s49, v[56:57]
	v_mad_u64_u32 v[118:119], s[6:7], v119, s49, v[56:57]
	v_mad_u64_u32 v[120:121], s[6:7], v121, s49, v[56:57]
	v_mad_u64_u32 v[122:123], s[6:7], v122, s49, v[56:57]
	s_waitcnt vmcnt(0)
	ds_write_b32 v0, v124
	ds_write_b32 v2, v125
	ds_write_b32 v4, v126
	ds_write_b32 v6, v127
	ds_write_b32 v8, v128
	ds_write_b32 v10, v129
	ds_write_b32 v12, v130
	ds_write_b32 v14, v131
	ds_write_b32 v88, v132
	ds_write_b32 v90, v133
	ds_write_b32 v112, v134
	ds_write_b32 v114, v135
	ds_write_b32 v116, v18
	ds_write_b32 v118, v136
	ds_write_b32 v120, v137
	ds_write_b32 v122, v138
	s_cbranch_scc1 .LBB0_91
	s_waitcnt lgkmcnt(0)
	ds_read2_b32 v[4:5], v94 offset1:8
	ds_read2_b32 v[8:9], v94 offset0:33 offset1:41
	ds_read2_b32 v[10:11], v94 offset0:66 offset1:74
	ds_read2_b32 v[12:13], v94 offset0:99 offset1:107
	ds_read2_b32 v[14:15], v94 offset0:132 offset1:140
	ds_read2_b32 v[88:89], v94 offset0:165 offset1:173
	s_waitcnt lgkmcnt(0)
	v_bfe_u32 v0, v4, 16, 1
	v_add3_u32 v0, v4, v0, s65
	v_bfe_u32 v1, v8, 16, 1
	v_lshrrev_b32_e32 v0, 16, v0
	v_add3_u32 v1, v8, v1, s65
	v_and_or_b32 v0, v1, s66, v0
	v_bfe_u32 v1, v10, 16, 1
	v_add3_u32 v1, v10, v1, s65
	v_bfe_u32 v2, v12, 16, 1
	ds_read2_b32 v[90:91], v94 offset0:198 offset1:206
	v_lshrrev_b32_e32 v1, 16, v1
	v_add3_u32 v2, v12, v2, s65
	ds_read2_b32 v[112:113], v94 offset0:231 offset1:239
	v_and_or_b32 v1, v2, s66, v1
	v_bfe_u32 v2, v14, 16, 1
	v_add3_u32 v2, v14, v2, s65
	v_bfe_u32 v3, v88, 16, 1
	v_lshrrev_b32_e32 v2, 16, v2
	v_add3_u32 v3, v88, v3, s65
	v_and_or_b32 v2, v3, s66, v2
	s_waitcnt lgkmcnt(1)
	v_bfe_u32 v3, v90, 16, 1
	s_mov_b32 s1, s25
	v_add3_u32 v3, v90, v3, s65
	s_waitcnt lgkmcnt(0)
	v_bfe_u32 v4, v112, 16, 1
	v_lshl_add_u64 v[6:7], s[0:1], 1, v[60:61]
	v_lshrrev_b32_e32 v3, 16, v3
	v_add3_u32 v4, v112, v4, s65
	v_mov_b32_e32 v73, v19
	v_and_or_b32 v3, v4, s66, v3
	v_lshl_add_u64 v[114:115], v[6:7], 0, v[72:73]
	global_store_dwordx4 v[114:115], v[0:3], off
	v_bfe_u32 v4, v113, 16, 1
	v_add3_u32 v4, v113, v4, s65
	v_bfe_u32 v0, v5, 16, 1
	v_add3_u32 v0, v5, v0, s65
	v_bfe_u32 v1, v9, 16, 1
	v_lshrrev_b32_e32 v0, 16, v0
	v_add3_u32 v1, v9, v1, s65
	v_and_or_b32 v0, v1, s66, v0
	v_bfe_u32 v1, v11, 16, 1
	v_add3_u32 v1, v11, v1, s65
	v_bfe_u32 v2, v13, 16, 1
	v_lshrrev_b32_e32 v1, 16, v1
	v_add3_u32 v2, v13, v2, s65
	v_and_or_b32 v1, v2, s66, v1
	v_bfe_u32 v2, v15, 16, 1
	v_add3_u32 v2, v15, v2, s65
	v_bfe_u32 v3, v89, 16, 1
	v_lshrrev_b32_e32 v2, 16, v2
	v_add3_u32 v3, v89, v3, s65
	v_and_or_b32 v2, v3, s66, v2
	v_bfe_u32 v3, v91, 16, 1
	v_add3_u32 v3, v91, v3, s65
	v_lshrrev_b32_e32 v3, 16, v3
	v_mov_b32_e32 v75, v19
	v_and_or_b32 v3, v4, s66, v3
	ds_read2_b32 v[4:5], v94 offset0:16 offset1:24
	v_lshl_add_u64 v[8:9], v[6:7], 0, v[74:75]
	global_store_dwordx4 v[8:9], v[0:3], off
	ds_read2_b32 v[8:9], v94 offset0:49 offset1:57
	ds_read2_b32 v[10:11], v94 offset0:82 offset1:90
	ds_read2_b32 v[12:13], v94 offset0:115 offset1:123
	s_waitcnt lgkmcnt(3)
	v_bfe_u32 v0, v4, 16, 1
	v_add3_u32 v0, v4, v0, s65
	s_waitcnt lgkmcnt(2)
	v_bfe_u32 v1, v8, 16, 1
	ds_read2_b32 v[14:15], v94 offset0:148 offset1:156
	v_lshrrev_b32_e32 v0, 16, v0
	v_add3_u32 v1, v8, v1, s65
	ds_read2_b32 v[88:89], v94 offset0:181 offset1:189
	v_and_or_b32 v0, v1, s66, v0
	s_waitcnt lgkmcnt(3)
	v_bfe_u32 v1, v10, 16, 1
	v_add3_u32 v1, v10, v1, s65
	s_waitcnt lgkmcnt(2)
	v_bfe_u32 v2, v12, 16, 1
	ds_read2_b32 v[90:91], v94 offset0:214 offset1:222
	v_lshrrev_b32_e32 v1, 16, v1
	v_add3_u32 v2, v12, v2, s65
	ds_read2_b32 v[112:113], v94 offset0:247 offset1:255
	v_and_or_b32 v1, v2, s66, v1
	s_waitcnt lgkmcnt(3)
	v_bfe_u32 v2, v14, 16, 1
	v_add3_u32 v2, v14, v2, s65
	s_waitcnt lgkmcnt(2)
	v_bfe_u32 v3, v88, 16, 1
	v_lshrrev_b32_e32 v2, 16, v2
	v_add3_u32 v3, v88, v3, s65
	v_and_or_b32 v2, v3, s66, v2
	s_waitcnt lgkmcnt(1)
	v_bfe_u32 v3, v90, 16, 1
	v_add3_u32 v3, v90, v3, s65
	s_waitcnt lgkmcnt(0)
	v_bfe_u32 v4, v112, 16, 1
	v_lshrrev_b32_e32 v3, 16, v3
	v_add3_u32 v4, v112, v4, s65
	v_mov_b32_e32 v77, v19
	v_and_or_b32 v3, v4, s66, v3
	v_lshl_add_u64 v[114:115], v[6:7], 0, v[76:77]
	global_store_dwordx4 v[114:115], v[0:3], off
	v_bfe_u32 v4, v113, 16, 1
	v_add3_u32 v4, v113, v4, s65
	v_bfe_u32 v0, v5, 16, 1
	v_add3_u32 v0, v5, v0, s65
	v_bfe_u32 v1, v9, 16, 1
	v_lshrrev_b32_e32 v0, 16, v0
	v_add3_u32 v1, v9, v1, s65
	v_and_or_b32 v0, v1, s66, v0
	v_bfe_u32 v1, v11, 16, 1
	v_add3_u32 v1, v11, v1, s65
	v_bfe_u32 v2, v13, 16, 1
	v_lshrrev_b32_e32 v1, 16, v1
	v_add3_u32 v2, v13, v2, s65
	v_and_or_b32 v1, v2, s66, v1
	v_bfe_u32 v2, v15, 16, 1
	v_add3_u32 v2, v15, v2, s65
	v_bfe_u32 v3, v89, 16, 1
	v_lshrrev_b32_e32 v2, 16, v2
	v_add3_u32 v3, v89, v3, s65
	v_and_or_b32 v2, v3, s66, v2
	v_bfe_u32 v3, v91, 16, 1
	v_add3_u32 v3, v91, v3, s65
	v_lshrrev_b32_e32 v3, 16, v3
	v_mov_b32_e32 v79, v19
	v_and_or_b32 v3, v4, s66, v3
	v_lshl_add_u64 v[4:5], v[6:7], 0, v[78:79]
	global_store_dwordx4 v[4:5], v[0:3], off
	s_waitcnt lgkmcnt(0)

.LBB0_96:
	s_lshl_b32 s7, s4, 1
	s_lshl_b32 s6, s3, 1
	v_or_b32_e32 v75, s7, v54
	s_add_i32 s26, s7, 4
	v_or_b32_e32 v73, s6, v17
	s_add_i32 s24, s6, 4
	s_add_i32 s71, s7, 8
	v_add_lshl_u32 v18, v75, s0, 9
	v_or_b32_e32 v79, s26, v54
	v_mov_b32_e32 v3, v19
	s_add_i32 s73, s7, 12
	v_add_lshl_u32 v2, v73, s1, 9
	v_or_b32_e32 v77, s24, v17
	v_or_b32_e32 v114, s71, v54
	v_lshl_add_u64 v[90:91], v[18:19], 2, v[0:1]
	v_add_lshl_u32 v18, v79, s0, 9
	v_mov_b32_e32 v5, v19
	s_add_i32 s27, s6, 8
	s_add_i32 s72, s6, 12
	s_add_i32 s75, s7, 16
	v_or_b32_e32 v116, s73, v54
	v_lshl_add_u64 v[2:3], v[2:3], 2, v[0:1]
	v_add_lshl_u32 v4, v77, s1, 9
	v_lshl_add_u64 v[112:113], v[18:19], 2, v[0:1]
	v_add_lshl_u32 v18, v114, s0, 9
	s_add_i32 s77, s7, 20
	v_or_b32_e32 v111, s27, v17
	v_or_b32_e32 v115, s72, v17
	v_or_b32_e32 v118, s75, v54
	v_lshl_add_u64 v[4:5], v[4:5], 2, v[0:1]
	global_load_dword v126, v[90:91], off nt
	global_load_dword v127, v[2:3], off nt
	global_load_dword v128, v[112:113], off nt
	global_load_dword v129, v[4:5], off nt
	v_lshl_add_u64 v[2:3], v[18:19], 2, v[0:1]
	v_add_lshl_u32 v18, v116, s0, 9
	v_mov_b32_e32 v7, v19
	v_mov_b32_e32 v9, v19
	s_add_i32 s74, s6, 16
	s_add_i32 s76, s6, 20
	s_add_i32 s79, s7, 24
	v_or_b32_e32 v120, s77, v54
	v_add_lshl_u32 v6, v111, s1, 9
	v_add_lshl_u32 v8, v115, s1, 9
	v_lshl_add_u64 v[4:5], v[18:19], 2, v[0:1]
	v_add_lshl_u32 v18, v118, s0, 9
	s_add_i32 s78, s6, 24
	s_add_i32 s6, s6, 28
	s_add_i32 s7, s7, 28
	v_or_b32_e32 v117, s74, v17
	v_or_b32_e32 v119, s76, v17
	v_or_b32_e32 v122, s79, v54
	v_lshl_add_u64 v[6:7], v[6:7], 2, v[0:1]
	v_lshl_add_u64 v[8:9], v[8:9], 2, v[0:1]
	global_load_dword v130, v[2:3], off nt
	global_load_dword v131, v[6:7], off nt
	global_load_dword v132, v[4:5], off nt
	global_load_dword v133, v[8:9], off nt
	v_lshl_add_u64 v[2:3], v[18:19], 2, v[0:1]
	v_add_lshl_u32 v18, v120, s0, 9
	v_mov_b32_e32 v11, v19
	v_mov_b32_e32 v13, v19
	v_or_b32_e32 v121, s78, v17
	v_or_b32_e32 v124, s6, v17
	v_or_b32_e32 v123, s7, v54
	v_add_lshl_u32 v10, v117, s1, 9
	v_add_lshl_u32 v12, v119, s1, 9
	v_lshl_add_u64 v[4:5], v[18:19], 2, v[0:1]
	v_add_lshl_u32 v18, v122, s0, 9
	v_mov_b32_e32 v15, v19
	v_mov_b32_e32 v89, v19
	v_add_lshl_u32 v14, v121, s1, 9
	v_add_lshl_u32 v88, v124, s1, 9
	v_lshl_add_u64 v[10:11], v[10:11], 2, v[0:1]
	v_lshl_add_u64 v[12:13], v[12:13], 2, v[0:1]
	global_load_dword v134, v[2:3], off nt
	global_load_dword v135, v[10:11], off nt
	global_load_dword v136, v[4:5], off nt
	global_load_dword v137, v[12:13], off nt
	v_lshl_add_u64 v[2:3], v[18:19], 2, v[0:1]
	v_add_lshl_u32 v18, v123, s0, 9
	v_lshl_add_u64 v[14:15], v[14:15], 2, v[0:1]
	v_lshl_add_u64 v[88:89], v[88:89], 2, v[0:1]
	v_lshl_add_u64 v[4:5], v[18:19], 2, v[0:1]
	global_load_dword v18, v[2:3], off nt
	global_load_dword v138, v[14:15], off nt
	global_load_dword v139, v[4:5], off nt
	global_load_dword v140, v[88:89], off nt
	s_add_i32 s4, s4, 16
	s_add_i32 s3, s3, 16
	s_add_i32 s5, s5, -16
	v_mad_u64_u32 v[2:3], s[6:7], v75, s49, v[56:57]
	s_cmp_lg_u32 s5, 0
	v_mad_u64_u32 v[4:5], s[6:7], v73, s49, v[56:57]
	v_mad_u64_u32 v[6:7], s[6:7], v79, s49, v[56:57]
	v_mad_u64_u32 v[8:9], s[6:7], v77, s49, v[56:57]
	v_mad_u64_u32 v[10:11], s[6:7], v114, s49, v[56:57]
	v_mad_u64_u32 v[12:13], s[6:7], v111, s49, v[56:57]
	v_mad_u64_u32 v[14:15], s[6:7], v116, s49, v[56:57]
	v_mad_u64_u32 v[88:89], s[6:7], v115, s49, v[56:57]
	v_mad_u64_u32 v[90:91], s[6:7], v118, s49, v[56:57]
	v_mad_u64_u32 v[112:113], s[6:7], v117, s49, v[56:57]
	v_mad_u64_u32 v[114:115], s[6:7], v120, s49, v[56:57]
	v_mad_u64_u32 v[116:117], s[6:7], v119, s49, v[56:57]
	v_mad_u64_u32 v[118:119], s[6:7], v122, s49, v[56:57]
	v_mad_u64_u32 v[120:121], s[6:7], v121, s49, v[56:57]
	v_mad_u64_u32 v[122:123], s[6:7], v123, s49, v[56:57]
	v_mad_u64_u32 v[124:125], s[6:7], v124, s49, v[56:57]
	s_waitcnt vmcnt(0)
	ds_write_b32 v2, v126
	ds_write_b32 v4, v127
	ds_write_b32 v6, v128
	ds_write_b32 v8, v129
	ds_write_b32 v10, v130
	ds_write_b32 v12, v131
	ds_write_b32 v14, v132
	ds_write_b32 v88, v133
	ds_write_b32 v90, v134
	ds_write_b32 v112, v135
	ds_write_b32 v114, v136
	ds_write_b32 v116, v137
	ds_write_b32 v118, v18
	ds_write_b32 v120, v138
	ds_write_b32 v122, v139
	ds_write_b32 v124, v140
	s_cbranch_scc1 .LBB0_96
	s_waitcnt lgkmcnt(0)
	ds_read2_b32 v[4:5], v94 offset1:8
	ds_read2_b32 v[8:9], v94 offset0:33 offset1:41
	ds_read2_b32 v[10:11], v94 offset0:66 offset1:74
	ds_read2_b32 v[12:13], v94 offset0:99 offset1:107
	ds_read2_b32 v[14:15], v94 offset0:132 offset1:140
	ds_read2_b32 v[88:89], v94 offset0:165 offset1:173
	s_waitcnt lgkmcnt(0)
	v_bfe_u32 v0, v4, 16, 1
	v_add3_u32 v0, v4, v0, s65
	v_bfe_u32 v1, v8, 16, 1
	v_lshrrev_b32_e32 v0, 16, v0
	v_add3_u32 v1, v8, v1, s65
	v_and_or_b32 v0, v1, s66, v0
	v_bfe_u32 v1, v10, 16, 1
	v_add3_u32 v1, v10, v1, s65
	v_bfe_u32 v2, v12, 16, 1
	ds_read2_b32 v[90:91], v94 offset0:198 offset1:206
	v_lshrrev_b32_e32 v1, 16, v1
	v_add3_u32 v2, v12, v2, s65
	ds_read2_b32 v[112:113], v94 offset0:231 offset1:239
	v_and_or_b32 v1, v2, s66, v1
	v_bfe_u32 v2, v14, 16, 1
	v_add3_u32 v2, v14, v2, s65
	v_bfe_u32 v3, v88, 16, 1
	v_lshrrev_b32_e32 v2, 16, v2
	v_add3_u32 v3, v88, v3, s65
	v_and_or_b32 v2, v3, s66, v2
	s_waitcnt lgkmcnt(1)
	v_bfe_u32 v3, v90, 16, 1
	v_add3_u32 v3, v90, v3, s65
	s_waitcnt lgkmcnt(0)
	v_bfe_u32 v4, v112, 16, 1
	v_lshrrev_b32_e32 v3, 16, v3
	v_add3_u32 v4, v112, v4, s65
	s_mov_b32 s1, s25
	v_and_or_b32 v3, v4, s66, v3
	v_or_b32_e32 v4, s2, v25
	v_lshl_add_u64 v[6:7], s[0:1], 1, v[60:61]
	v_lshlrev_b32_e32 v18, 12, v4
	v_lshl_add_u64 v[114:115], v[6:7], 0, v[18:19]
	global_store_dwordx4 v[114:115], v[0:3], off
	v_bfe_u32 v4, v113, 16, 1
	v_or_b32_e32 v8, s2, v33
	v_bfe_u32 v0, v5, 16, 1
	v_add3_u32 v0, v5, v0, s65
	v_bfe_u32 v1, v9, 16, 1
	v_lshrrev_b32_e32 v0, 16, v0
	v_add3_u32 v1, v9, v1, s65
	v_and_or_b32 v0, v1, s66, v0
	v_bfe_u32 v1, v11, 16, 1
	v_add3_u32 v1, v11, v1, s65
	v_bfe_u32 v2, v13, 16, 1
	v_lshrrev_b32_e32 v1, 16, v1
	v_add3_u32 v2, v13, v2, s65
	v_and_or_b32 v1, v2, s66, v1
	v_bfe_u32 v2, v15, 16, 1
	v_add3_u32 v2, v15, v2, s65
	v_bfe_u32 v3, v89, 16, 1
	v_lshrrev_b32_e32 v2, 16, v2
	v_add3_u32 v3, v89, v3, s65
	v_and_or_b32 v2, v3, s66, v2
	v_bfe_u32 v3, v91, 16, 1
	v_add3_u32 v3, v91, v3, s65
	v_lshrrev_b32_e32 v3, 16, v3
	v_add3_u32 v4, v113, v4, s65
	v_lshlrev_b32_e32 v18, 12, v8
	v_and_or_b32 v3, v4, s66, v3
	ds_read2_b32 v[4:5], v94 offset0:16 offset1:24
	v_lshl_add_u64 v[8:9], v[6:7], 0, v[18:19]
	global_store_dwordx4 v[8:9], v[0:3], off
	ds_read2_b32 v[8:9], v94 offset0:49 offset1:57
	ds_read2_b32 v[10:11], v94 offset0:82 offset1:90
	ds_read2_b32 v[12:13], v94 offset0:115 offset1:123
	s_waitcnt lgkmcnt(3)
	v_bfe_u32 v0, v4, 16, 1
	v_add3_u32 v0, v4, v0, s65
	s_waitcnt lgkmcnt(2)
	v_bfe_u32 v1, v8, 16, 1
	ds_read2_b32 v[14:15], v94 offset0:148 offset1:156
	v_lshrrev_b32_e32 v0, 16, v0
	v_add3_u32 v1, v8, v1, s65
	ds_read2_b32 v[88:89], v94 offset0:181 offset1:189
	v_and_or_b32 v0, v1, s66, v0
	s_waitcnt lgkmcnt(3)
	v_bfe_u32 v1, v10, 16, 1
	v_add3_u32 v1, v10, v1, s65
	s_waitcnt lgkmcnt(2)
	v_bfe_u32 v2, v12, 16, 1
	ds_read2_b32 v[90:91], v94 offset0:214 offset1:222
	v_lshrrev_b32_e32 v1, 16, v1
	v_add3_u32 v2, v12, v2, s65
	ds_read2_b32 v[112:113], v94 offset0:247 offset1:255
	v_and_or_b32 v1, v2, s66, v1
	s_waitcnt lgkmcnt(3)
	v_bfe_u32 v2, v14, 16, 1
	v_add3_u32 v2, v14, v2, s65
	s_waitcnt lgkmcnt(2)
	v_bfe_u32 v3, v88, 16, 1
	v_lshrrev_b32_e32 v2, 16, v2
	v_add3_u32 v3, v88, v3, s65
	v_and_or_b32 v2, v3, s66, v2
	s_waitcnt lgkmcnt(1)
	v_bfe_u32 v3, v90, 16, 1
	v_add3_u32 v3, v90, v3, s65
	s_waitcnt lgkmcnt(0)
	v_bfe_u32 v4, v112, 16, 1
	v_lshrrev_b32_e32 v3, 16, v3
	v_add3_u32 v4, v112, v4, s65
	v_and_or_b32 v3, v4, s66, v3
	v_or_b32_e32 v4, s2, v55
	v_lshlrev_b32_e32 v18, 12, v4
	v_lshl_add_u64 v[114:115], v[6:7], 0, v[18:19]
	global_store_dwordx4 v[114:115], v[0:3], off
	v_bfe_u32 v4, v113, 16, 1
	v_add3_u32 v4, v113, v4, s65
	v_bfe_u32 v0, v5, 16, 1
	v_add3_u32 v0, v5, v0, s65
	v_bfe_u32 v1, v9, 16, 1
	v_lshrrev_b32_e32 v0, 16, v0
	v_add3_u32 v1, v9, v1, s65
	v_and_or_b32 v0, v1, s66, v0
	v_bfe_u32 v1, v11, 16, 1
	v_add3_u32 v1, v11, v1, s65
	v_bfe_u32 v2, v13, 16, 1
	v_lshrrev_b32_e32 v1, 16, v1
	v_add3_u32 v2, v13, v2, s65
	v_and_or_b32 v1, v2, s66, v1
	v_bfe_u32 v2, v15, 16, 1
	v_add3_u32 v2, v15, v2, s65
	v_bfe_u32 v3, v89, 16, 1
	v_lshrrev_b32_e32 v2, 16, v2
	v_add3_u32 v3, v89, v3, s65
	v_and_or_b32 v2, v3, s66, v2
	v_bfe_u32 v3, v91, 16, 1
	v_add3_u32 v3, v91, v3, s65
	v_lshrrev_b32_e32 v3, 16, v3
	v_and_or_b32 v3, v4, s66, v3
	v_or_b32_e32 v4, s2, v57
	v_lshlrev_b32_e32 v18, 12, v4
	v_lshl_add_u64 v[4:5], v[6:7], 0, v[18:19]
	global_store_dwordx4 v[4:5], v[0:3], off
	s_waitcnt lgkmcnt(0)

.LBB0_101:
	s_lshl_b32 s26, s5, 1
	s_lshl_b32 s7, s4, 1
	v_or_b32_e32 v75, s26, v54
	s_add_i32 s71, s26, 4
	v_or_b32_e32 v73, s7, v17
	s_add_i32 s27, s7, 4
	s_add_i32 s73, s26, 8
	v_add_lshl_u32 v18, v75, s0, 9
	v_or_b32_e32 v79, s71, v54
	v_mov_b32_e32 v3, v19
	s_add_i32 s75, s26, 12
	v_add_lshl_u32 v2, v73, s3, 9
	v_or_b32_e32 v77, s27, v17
	v_or_b32_e32 v114, s73, v54
	v_lshl_add_u64 v[90:91], v[18:19], 2, v[0:1]
	v_add_lshl_u32 v18, v79, s0, 9
	v_mov_b32_e32 v5, v19
	s_add_i32 s72, s7, 8
	s_add_i32 s74, s7, 12
	s_add_i32 s77, s26, 16
	v_or_b32_e32 v116, s75, v54
	v_lshl_add_u64 v[2:3], v[2:3], 2, v[0:1]
	v_add_lshl_u32 v4, v77, s3, 9
	v_lshl_add_u64 v[112:113], v[18:19], 2, v[0:1]
	v_add_lshl_u32 v18, v114, s0, 9
	s_add_i32 s79, s26, 20
	v_or_b32_e32 v111, s72, v17
	v_or_b32_e32 v115, s74, v17
	v_or_b32_e32 v118, s77, v54
	v_lshl_add_u64 v[4:5], v[4:5], 2, v[0:1]
	global_load_dword v126, v[90:91], off nt
	global_load_dword v127, v[2:3], off nt
	global_load_dword v128, v[112:113], off nt
	global_load_dword v129, v[4:5], off nt
	v_lshl_add_u64 v[2:3], v[18:19], 2, v[0:1]
	v_add_lshl_u32 v18, v116, s0, 9
	v_mov_b32_e32 v7, v19
	v_mov_b32_e32 v9, v19
	s_add_i32 s76, s7, 16
	s_add_i32 s78, s7, 20
	s_add_i32 s81, s26, 24
	v_or_b32_e32 v120, s79, v54
	v_add_lshl_u32 v6, v111, s3, 9
	v_add_lshl_u32 v8, v115, s3, 9
	v_lshl_add_u64 v[4:5], v[18:19], 2, v[0:1]
	v_add_lshl_u32 v18, v118, s0, 9
	s_add_i32 s80, s7, 24
	s_add_i32 s7, s7, 28
	s_add_i32 s26, s26, 28
	v_or_b32_e32 v117, s76, v17
	v_or_b32_e32 v119, s78, v17
	v_or_b32_e32 v122, s81, v54
	v_lshl_add_u64 v[6:7], v[6:7], 2, v[0:1]
	v_lshl_add_u64 v[8:9], v[8:9], 2, v[0:1]
	global_load_dword v130, v[2:3], off nt
	global_load_dword v131, v[6:7], off nt
	global_load_dword v132, v[4:5], off nt
	global_load_dword v133, v[8:9], off nt
	v_lshl_add_u64 v[2:3], v[18:19], 2, v[0:1]
	v_add_lshl_u32 v18, v120, s0, 9
	v_mov_b32_e32 v11, v19
	v_mov_b32_e32 v13, v19
	v_or_b32_e32 v121, s80, v17
	v_or_b32_e32 v124, s7, v17
	v_or_b32_e32 v123, s26, v54
	v_add_lshl_u32 v10, v117, s3, 9
	v_add_lshl_u32 v12, v119, s3, 9
	v_lshl_add_u64 v[4:5], v[18:19], 2, v[0:1]
	v_add_lshl_u32 v18, v122, s0, 9
	v_mov_b32_e32 v15, v19
	v_mov_b32_e32 v89, v19
	v_add_lshl_u32 v14, v121, s3, 9
	v_add_lshl_u32 v88, v124, s3, 9
	v_lshl_add_u64 v[10:11], v[10:11], 2, v[0:1]
	v_lshl_add_u64 v[12:13], v[12:13], 2, v[0:1]
	global_load_dword v134, v[2:3], off nt
	global_load_dword v135, v[10:11], off nt
	global_load_dword v136, v[4:5], off nt
	global_load_dword v137, v[12:13], off nt
	v_lshl_add_u64 v[2:3], v[18:19], 2, v[0:1]
	v_add_lshl_u32 v18, v123, s0, 9
	v_lshl_add_u64 v[14:15], v[14:15], 2, v[0:1]
	v_lshl_add_u64 v[88:89], v[88:89], 2, v[0:1]
	v_lshl_add_u64 v[4:5], v[18:19], 2, v[0:1]
	global_load_dword v18, v[2:3], off nt
	global_load_dword v138, v[14:15], off nt
	global_load_dword v139, v[4:5], off nt
	global_load_dword v140, v[88:89], off nt
	s_add_i32 s5, s5, 16
	s_add_i32 s4, s4, 16
	s_add_i32 s6, s6, -16
	v_mad_u64_u32 v[2:3], s[26:27], v75, s49, v[56:57]
	s_cmp_lg_u32 s6, 0
	v_mad_u64_u32 v[4:5], s[26:27], v73, s49, v[56:57]
	v_mad_u64_u32 v[6:7], s[26:27], v79, s49, v[56:57]
	v_mad_u64_u32 v[8:9], s[26:27], v77, s49, v[56:57]
	v_mad_u64_u32 v[10:11], s[26:27], v114, s49, v[56:57]
	v_mad_u64_u32 v[12:13], s[26:27], v111, s49, v[56:57]
	v_mad_u64_u32 v[14:15], s[26:27], v116, s49, v[56:57]
	v_mad_u64_u32 v[88:89], s[26:27], v115, s49, v[56:57]
	v_mad_u64_u32 v[90:91], s[26:27], v118, s49, v[56:57]
	v_mad_u64_u32 v[112:113], s[26:27], v117, s49, v[56:57]
	v_mad_u64_u32 v[114:115], s[26:27], v120, s49, v[56:57]
	v_mad_u64_u32 v[116:117], s[26:27], v119, s49, v[56:57]
	v_mad_u64_u32 v[118:119], s[26:27], v122, s49, v[56:57]
	v_mad_u64_u32 v[120:121], s[26:27], v121, s49, v[56:57]
	v_mad_u64_u32 v[122:123], s[26:27], v123, s49, v[56:57]
	v_mad_u64_u32 v[124:125], s[26:27], v124, s49, v[56:57]
	s_waitcnt vmcnt(0)
	ds_write_b32 v2, v126
	ds_write_b32 v4, v127
	ds_write_b32 v6, v128
	ds_write_b32 v8, v129
	ds_write_b32 v10, v130
	ds_write_b32 v12, v131
	ds_write_b32 v14, v132
	ds_write_b32 v88, v133
	ds_write_b32 v90, v134
	ds_write_b32 v112, v135
	ds_write_b32 v114, v136
	ds_write_b32 v116, v137
	ds_write_b32 v118, v18
	ds_write_b32 v120, v138
	ds_write_b32 v122, v139
	ds_write_b32 v124, v140
	s_cbranch_scc1 .LBB0_101
	s_waitcnt lgkmcnt(0)
	ds_read2_b32 v[4:5], v94 offset1:8
	ds_read2_b32 v[8:9], v94 offset0:33 offset1:41
	ds_read2_b32 v[10:11], v94 offset0:66 offset1:74
	ds_read2_b32 v[12:13], v94 offset0:99 offset1:107
	ds_read2_b32 v[14:15], v94 offset0:132 offset1:140
	s_waitcnt lgkmcnt(0)
	v_bfe_u32 v0, v4, 16, 1
	v_add3_u32 v0, v4, v0, s65
	v_bfe_u32 v1, v8, 16, 1
	v_lshrrev_b32_e32 v0, 16, v0
	v_add3_u32 v1, v8, v1, s65
	ds_read2_b32 v[88:89], v94 offset0:165 offset1:173
	v_and_or_b32 v0, v1, s66, v0
	v_bfe_u32 v1, v10, 16, 1
	v_add3_u32 v1, v10, v1, s65
	v_bfe_u32 v2, v12, 16, 1
	ds_read2_b32 v[90:91], v94 offset0:198 offset1:206
	v_lshrrev_b32_e32 v1, 16, v1
	v_add3_u32 v2, v12, v2, s65
	ds_read2_b32 v[112:113], v94 offset0:231 offset1:239
	v_and_or_b32 v1, v2, s66, v1
	v_bfe_u32 v2, v14, 16, 1
	s_lshr_b32 s4, s1, 9
	s_mov_b32 s5, s25
	s_lshl_b32 s1, s24, 9
	v_add3_u32 v2, v14, v2, s65
	s_waitcnt lgkmcnt(2)
	v_bfe_u32 v3, v88, 16, 1
	s_lshl_b64 s[4:5], s[4:5], 21
	s_and_b32 s1, s1, 0x600
	v_lshrrev_b32_e32 v2, 16, v2
	v_add3_u32 v3, v88, v3, s65
	s_add_u32 s3, s40, s4
	v_and_or_b32 v2, v3, s66, v2
	s_waitcnt lgkmcnt(1)
	v_bfe_u32 v3, v90, 16, 1
	s_addc_u32 s4, s41, s5
	s_or_b32 s2, s1, s2
	s_lshl_b32 s0, s0, 1
	v_add3_u32 v3, v90, v3, s65
	s_waitcnt lgkmcnt(0)
	v_bfe_u32 v4, v112, 16, 1
	s_add_u32 s0, s3, s0
	v_lshrrev_b32_e32 v3, 16, v3
	v_add3_u32 v4, v112, v4, s65
	s_addc_u32 s1, s4, 0
	v_lshlrev_b32_e32 v18, 1, v24
	v_and_or_b32 v3, v4, s66, v3
	v_or_b32_e32 v4, s2, v25
	v_lshl_add_u64 v[6:7], s[0:1], 0, v[18:19]
	v_lshlrev_b32_e32 v18, 10, v4
	v_lshl_add_u64 v[114:115], v[6:7], 0, v[18:19]
	global_store_dwordx4 v[114:115], v[0:3], off
	v_bfe_u32 v4, v113, 16, 1
	v_or_b32_e32 v8, s2, v33
	v_bfe_u32 v0, v5, 16, 1
	v_add3_u32 v0, v5, v0, s65
	v_bfe_u32 v1, v9, 16, 1
	v_lshrrev_b32_e32 v0, 16, v0
	v_add3_u32 v1, v9, v1, s65
	v_and_or_b32 v0, v1, s66, v0
	v_bfe_u32 v1, v11, 16, 1
	v_add3_u32 v1, v11, v1, s65
	v_bfe_u32 v2, v13, 16, 1
	v_lshrrev_b32_e32 v1, 16, v1
	v_add3_u32 v2, v13, v2, s65
	v_and_or_b32 v1, v2, s66, v1
	v_bfe_u32 v2, v15, 16, 1
	v_add3_u32 v2, v15, v2, s65
	v_bfe_u32 v3, v89, 16, 1
	v_lshrrev_b32_e32 v2, 16, v2
	v_add3_u32 v3, v89, v3, s65
	v_and_or_b32 v2, v3, s66, v2
	v_bfe_u32 v3, v91, 16, 1
	v_add3_u32 v3, v91, v3, s65
	v_lshrrev_b32_e32 v3, 16, v3
	v_add3_u32 v4, v113, v4, s65
	v_lshlrev_b32_e32 v18, 10, v8
	v_and_or_b32 v3, v4, s66, v3
	ds_read2_b32 v[4:5], v94 offset0:16 offset1:24
	v_lshl_add_u64 v[8:9], v[6:7], 0, v[18:19]
	global_store_dwordx4 v[8:9], v[0:3], off
	ds_read2_b32 v[8:9], v94 offset0:49 offset1:57
	ds_read2_b32 v[10:11], v94 offset0:82 offset1:90
	ds_read2_b32 v[12:13], v94 offset0:115 offset1:123
	s_waitcnt lgkmcnt(3)
	v_bfe_u32 v0, v4, 16, 1
	v_add3_u32 v0, v4, v0, s65
	s_waitcnt lgkmcnt(2)
	v_bfe_u32 v1, v8, 16, 1
	ds_read2_b32 v[14:15], v94 offset0:148 offset1:156
	v_lshrrev_b32_e32 v0, 16, v0
	v_add3_u32 v1, v8, v1, s65
	ds_read2_b32 v[88:89], v94 offset0:181 offset1:189
	v_and_or_b32 v0, v1, s66, v0
	s_waitcnt lgkmcnt(3)
	v_bfe_u32 v1, v10, 16, 1
	v_add3_u32 v1, v10, v1, s65
	s_waitcnt lgkmcnt(2)
	v_bfe_u32 v2, v12, 16, 1
	ds_read2_b32 v[90:91], v94 offset0:214 offset1:222
	v_lshrrev_b32_e32 v1, 16, v1
	v_add3_u32 v2, v12, v2, s65
	ds_read2_b32 v[112:113], v94 offset0:247 offset1:255
	v_and_or_b32 v1, v2, s66, v1
	s_waitcnt lgkmcnt(3)
	v_bfe_u32 v2, v14, 16, 1
	v_add3_u32 v2, v14, v2, s65
	s_waitcnt lgkmcnt(2)
	v_bfe_u32 v3, v88, 16, 1
	v_lshrrev_b32_e32 v2, 16, v2
	v_add3_u32 v3, v88, v3, s65
	v_and_or_b32 v2, v3, s66, v2
	s_waitcnt lgkmcnt(1)
	v_bfe_u32 v3, v90, 16, 1
	v_add3_u32 v3, v90, v3, s65
	s_waitcnt lgkmcnt(0)
	v_bfe_u32 v4, v112, 16, 1
	v_lshrrev_b32_e32 v3, 16, v3
	v_add3_u32 v4, v112, v4, s65
	v_and_or_b32 v3, v4, s66, v3
	v_or_b32_e32 v4, s2, v55
	v_lshlrev_b32_e32 v18, 10, v4
	v_lshl_add_u64 v[114:115], v[6:7], 0, v[18:19]
	global_store_dwordx4 v[114:115], v[0:3], off
	v_bfe_u32 v4, v113, 16, 1
	v_add3_u32 v4, v113, v4, s65
	v_bfe_u32 v0, v5, 16, 1
	v_add3_u32 v0, v5, v0, s65
	v_bfe_u32 v1, v9, 16, 1
	v_lshrrev_b32_e32 v0, 16, v0
	v_add3_u32 v1, v9, v1, s65
	v_and_or_b32 v0, v1, s66, v0
	v_bfe_u32 v1, v11, 16, 1
	v_add3_u32 v1, v11, v1, s65
	v_bfe_u32 v2, v13, 16, 1
	v_lshrrev_b32_e32 v1, 16, v1
	v_add3_u32 v2, v13, v2, s65
	v_and_or_b32 v1, v2, s66, v1
	v_bfe_u32 v2, v15, 16, 1
	v_add3_u32 v2, v15, v2, s65
	v_bfe_u32 v3, v89, 16, 1
	v_lshrrev_b32_e32 v2, 16, v2
	v_add3_u32 v3, v89, v3, s65
	v_and_or_b32 v2, v3, s66, v2
	v_bfe_u32 v3, v91, 16, 1
	v_add3_u32 v3, v91, v3, s65
	v_lshrrev_b32_e32 v3, 16, v3
	v_and_or_b32 v3, v4, s66, v3
	v_or_b32_e32 v4, s2, v57
	v_lshlrev_b32_e32 v18, 10, v4
	v_lshl_add_u64 v[4:5], v[6:7], 0, v[18:19]
	global_store_dwordx4 v[4:5], v[0:3], off
	s_waitcnt lgkmcnt(0)

.LBB0_106:
	s_lshl_b32 s24, s5, 1
	s_lshl_b32 s7, s4, 1
	v_or_b32_e32 v75, s24, v54
	s_add_i32 s27, s24, 4
	v_or_b32_e32 v73, s7, v17
	s_add_i32 s26, s7, 4
	s_add_i32 s72, s24, 8
	v_add_lshl_u32 v18, v75, s1, 11
	v_or_b32_e32 v79, s27, v54
	v_mov_b32_e32 v3, v19
	s_add_i32 s74, s24, 12
	v_add_lshl_u32 v2, v73, s3, 11
	v_or_b32_e32 v77, s26, v17
	v_or_b32_e32 v114, s72, v54
	v_lshl_add_u64 v[90:91], v[18:19], 2, v[0:1]
	v_add_lshl_u32 v18, v79, s1, 11
	v_mov_b32_e32 v5, v19
	s_add_i32 s71, s7, 8
	s_add_i32 s73, s7, 12
	s_add_i32 s76, s24, 16
	v_or_b32_e32 v116, s74, v54
	v_lshl_add_u64 v[2:3], v[2:3], 2, v[0:1]
	v_add_lshl_u32 v4, v77, s3, 11
	v_lshl_add_u64 v[112:113], v[18:19], 2, v[0:1]
	v_add_lshl_u32 v18, v114, s1, 11
	s_add_i32 s78, s24, 20
	v_or_b32_e32 v111, s71, v17
	v_or_b32_e32 v115, s73, v17
	v_or_b32_e32 v118, s76, v54
	v_lshl_add_u64 v[4:5], v[4:5], 2, v[0:1]
	global_load_dword v126, v[90:91], off nt
	global_load_dword v127, v[2:3], off nt
	global_load_dword v128, v[112:113], off nt
	global_load_dword v129, v[4:5], off nt
	v_lshl_add_u64 v[2:3], v[18:19], 2, v[0:1]
	v_add_lshl_u32 v18, v116, s1, 11
	v_mov_b32_e32 v7, v19
	v_mov_b32_e32 v9, v19
	s_add_i32 s75, s7, 16
	s_add_i32 s77, s7, 20
	s_add_i32 s80, s24, 24
	v_or_b32_e32 v120, s78, v54
	v_add_lshl_u32 v6, v111, s3, 11
	v_add_lshl_u32 v8, v115, s3, 11
	v_lshl_add_u64 v[4:5], v[18:19], 2, v[0:1]
	v_add_lshl_u32 v18, v118, s1, 11
	s_add_i32 s79, s7, 24
	s_add_i32 s7, s7, 28
	s_add_i32 s24, s24, 28
	v_or_b32_e32 v117, s75, v17
	v_or_b32_e32 v119, s77, v17
	v_or_b32_e32 v122, s80, v54
	v_lshl_add_u64 v[6:7], v[6:7], 2, v[0:1]
	v_lshl_add_u64 v[8:9], v[8:9], 2, v[0:1]
	global_load_dword v130, v[2:3], off nt
	global_load_dword v131, v[6:7], off nt
	global_load_dword v132, v[4:5], off nt
	global_load_dword v133, v[8:9], off nt
	v_lshl_add_u64 v[2:3], v[18:19], 2, v[0:1]
	v_add_lshl_u32 v18, v120, s1, 11
	v_mov_b32_e32 v11, v19
	v_mov_b32_e32 v13, v19
	v_or_b32_e32 v121, s79, v17
	v_or_b32_e32 v124, s7, v17
	v_or_b32_e32 v123, s24, v54
	v_add_lshl_u32 v10, v117, s3, 11
	v_add_lshl_u32 v12, v119, s3, 11
	v_lshl_add_u64 v[4:5], v[18:19], 2, v[0:1]
	v_add_lshl_u32 v18, v122, s1, 11
	v_mov_b32_e32 v15, v19
	v_mov_b32_e32 v89, v19
	v_add_lshl_u32 v14, v121, s3, 11
	v_add_lshl_u32 v88, v124, s3, 11
	v_lshl_add_u64 v[10:11], v[10:11], 2, v[0:1]
	v_lshl_add_u64 v[12:13], v[12:13], 2, v[0:1]
	global_load_dword v134, v[2:3], off nt
	global_load_dword v135, v[10:11], off nt
	global_load_dword v136, v[4:5], off nt
	global_load_dword v137, v[12:13], off nt
	v_lshl_add_u64 v[2:3], v[18:19], 2, v[0:1]
	v_add_lshl_u32 v18, v123, s1, 11
	v_lshl_add_u64 v[14:15], v[14:15], 2, v[0:1]
	v_lshl_add_u64 v[88:89], v[88:89], 2, v[0:1]
	v_lshl_add_u64 v[4:5], v[18:19], 2, v[0:1]
	global_load_dword v18, v[2:3], off nt
	global_load_dword v138, v[14:15], off nt
	global_load_dword v139, v[4:5], off nt
	global_load_dword v140, v[88:89], off nt
	s_add_i32 s5, s5, 16
	s_add_i32 s4, s4, 16
	s_add_i32 s6, s6, -16
	v_mad_u64_u32 v[2:3], s[26:27], v75, s49, v[56:57]
	s_cmp_lg_u32 s6, 0
	v_mad_u64_u32 v[4:5], s[26:27], v73, s49, v[56:57]
	v_mad_u64_u32 v[6:7], s[26:27], v79, s49, v[56:57]
	v_mad_u64_u32 v[8:9], s[26:27], v77, s49, v[56:57]
	v_mad_u64_u32 v[10:11], s[26:27], v114, s49, v[56:57]
	v_mad_u64_u32 v[12:13], s[26:27], v111, s49, v[56:57]
	v_mad_u64_u32 v[14:15], s[26:27], v116, s49, v[56:57]
	v_mad_u64_u32 v[88:89], s[26:27], v115, s49, v[56:57]
	v_mad_u64_u32 v[90:91], s[26:27], v118, s49, v[56:57]
	v_mad_u64_u32 v[112:113], s[26:27], v117, s49, v[56:57]
	v_mad_u64_u32 v[114:115], s[26:27], v120, s49, v[56:57]
	v_mad_u64_u32 v[116:117], s[26:27], v119, s49, v[56:57]
	v_mad_u64_u32 v[118:119], s[26:27], v122, s49, v[56:57]
	v_mad_u64_u32 v[120:121], s[26:27], v121, s49, v[56:57]
	v_mad_u64_u32 v[122:123], s[26:27], v123, s49, v[56:57]
	v_mad_u64_u32 v[124:125], s[26:27], v124, s49, v[56:57]
	s_waitcnt vmcnt(0)
	ds_write_b32 v2, v126
	ds_write_b32 v4, v127
	ds_write_b32 v6, v128
	ds_write_b32 v8, v129
	ds_write_b32 v10, v130
	ds_write_b32 v12, v131
	ds_write_b32 v14, v132
	ds_write_b32 v88, v133
	ds_write_b32 v90, v134
	ds_write_b32 v112, v135
	ds_write_b32 v114, v136
	ds_write_b32 v116, v137
	ds_write_b32 v118, v18
	ds_write_b32 v120, v138
	ds_write_b32 v122, v139
	ds_write_b32 v124, v140
	s_cbranch_scc1 .LBB0_106
	s_waitcnt lgkmcnt(0)
	ds_read2_b32 v[4:5], v94 offset1:8
	ds_read2_b32 v[8:9], v94 offset0:33 offset1:41
	ds_read2_b32 v[10:11], v94 offset0:66 offset1:74
	ds_read2_b32 v[12:13], v94 offset0:99 offset1:107
	ds_read2_b32 v[14:15], v94 offset0:132 offset1:140
	s_waitcnt lgkmcnt(0)
	v_bfe_u32 v0, v4, 16, 1
	v_add3_u32 v0, v4, v0, s65
	v_bfe_u32 v1, v8, 16, 1
	v_lshrrev_b32_e32 v0, 16, v0
	v_add3_u32 v1, v8, v1, s65
	ds_read2_b32 v[88:89], v94 offset0:165 offset1:173
	v_and_or_b32 v0, v1, s66, v0
	v_bfe_u32 v1, v10, 16, 1
	v_add3_u32 v1, v10, v1, s65
	v_bfe_u32 v2, v12, 16, 1
	ds_read2_b32 v[90:91], v94 offset0:198 offset1:206
	v_lshrrev_b32_e32 v1, 16, v1
	v_add3_u32 v2, v12, v2, s65
	ds_read2_b32 v[112:113], v94 offset0:231 offset1:239
	v_and_or_b32 v1, v2, s66, v1
	v_bfe_u32 v2, v14, 16, 1
	v_add3_u32 v2, v14, v2, s65
	s_waitcnt lgkmcnt(2)
	v_bfe_u32 v3, v88, 16, 1
	v_lshrrev_b32_e32 v2, 16, v2
	v_add3_u32 v3, v88, v3, s65
	s_mul_i32 s2, s2, 0x1600000
	v_and_or_b32 v2, v3, s66, v2
	s_waitcnt lgkmcnt(1)
	v_bfe_u32 v3, v90, 16, 1
	s_add_u32 s2, s42, s2
	v_add3_u32 v3, v90, v3, s65
	s_waitcnt lgkmcnt(0)
	v_bfe_u32 v4, v112, 16, 1
	s_addc_u32 s3, s43, 0
	s_lshl_b32 s1, s1, 1
	v_lshrrev_b32_e32 v3, 16, v3
	v_add3_u32 v4, v112, v4, s65
	s_add_u32 s2, s2, s1
	v_and_or_b32 v3, v4, s66, v3
	v_or_b32_e32 v4, s0, v25
	s_addc_u32 s3, s3, 0
	v_lshlrev_b32_e32 v18, 1, v24
	v_mul_u32_u24_e32 v4, 0x1600, v4
	v_lshl_add_u64 v[6:7], s[2:3], 0, v[18:19]
	v_lshlrev_b32_e32 v18, 1, v4
	v_lshl_add_u64 v[114:115], v[6:7], 0, v[18:19]
	global_store_dwordx4 v[114:115], v[0:3], off
	v_bfe_u32 v4, v113, 16, 1
	v_add3_u32 v4, v113, v4, s65
	v_bfe_u32 v0, v5, 16, 1
	v_add3_u32 v0, v5, v0, s65
	v_bfe_u32 v1, v9, 16, 1
	v_lshrrev_b32_e32 v0, 16, v0
	v_add3_u32 v1, v9, v1, s65
	v_and_or_b32 v0, v1, s66, v0
	v_bfe_u32 v1, v11, 16, 1
	v_add3_u32 v1, v11, v1, s65
	v_bfe_u32 v2, v13, 16, 1
	v_lshrrev_b32_e32 v1, 16, v1
	v_add3_u32 v2, v13, v2, s65
	v_and_or_b32 v1, v2, s66, v1
	v_bfe_u32 v2, v15, 16, 1
	v_add3_u32 v2, v15, v2, s65
	v_bfe_u32 v3, v89, 16, 1
	v_lshrrev_b32_e32 v2, 16, v2
	v_add3_u32 v3, v89, v3, s65
	v_and_or_b32 v2, v3, s66, v2
	v_bfe_u32 v3, v91, 16, 1
	v_add3_u32 v3, v91, v3, s65
	v_lshrrev_b32_e32 v3, 16, v3
	v_and_or_b32 v3, v4, s66, v3
	v_or_b32_e32 v4, s0, v33
	v_mul_u32_u24_e32 v8, 0x1600, v4
	v_lshlrev_b32_e32 v18, 1, v8
	ds_read2_b32 v[4:5], v94 offset0:16 offset1:24
	v_lshl_add_u64 v[8:9], v[6:7], 0, v[18:19]
	global_store_dwordx4 v[8:9], v[0:3], off
	ds_read2_b32 v[8:9], v94 offset0:49 offset1:57
	ds_read2_b32 v[10:11], v94 offset0:82 offset1:90
	ds_read2_b32 v[12:13], v94 offset0:115 offset1:123
	s_waitcnt lgkmcnt(3)
	v_bfe_u32 v0, v4, 16, 1
	v_add3_u32 v0, v4, v0, s65
	s_waitcnt lgkmcnt(2)
	v_bfe_u32 v1, v8, 16, 1
	ds_read2_b32 v[14:15], v94 offset0:148 offset1:156
	v_lshrrev_b32_e32 v0, 16, v0
	v_add3_u32 v1, v8, v1, s65
	ds_read2_b32 v[88:89], v94 offset0:181 offset1:189
	v_and_or_b32 v0, v1, s66, v0
	s_waitcnt lgkmcnt(3)
	v_bfe_u32 v1, v10, 16, 1
	v_add3_u32 v1, v10, v1, s65
	s_waitcnt lgkmcnt(2)
	v_bfe_u32 v2, v12, 16, 1
	ds_read2_b32 v[90:91], v94 offset0:214 offset1:222
	v_lshrrev_b32_e32 v1, 16, v1
	v_add3_u32 v2, v12, v2, s65
	ds_read2_b32 v[112:113], v94 offset0:247 offset1:255
	v_and_or_b32 v1, v2, s66, v1
	s_waitcnt lgkmcnt(3)
	v_bfe_u32 v2, v14, 16, 1
	v_add3_u32 v2, v14, v2, s65
	s_waitcnt lgkmcnt(2)
	v_bfe_u32 v3, v88, 16, 1
	v_lshrrev_b32_e32 v2, 16, v2
	v_add3_u32 v3, v88, v3, s65
	v_and_or_b32 v2, v3, s66, v2
	s_waitcnt lgkmcnt(1)
	v_bfe_u32 v3, v90, 16, 1
	v_add3_u32 v3, v90, v3, s65
	s_waitcnt lgkmcnt(0)
	v_bfe_u32 v4, v112, 16, 1
	v_lshrrev_b32_e32 v3, 16, v3
	v_add3_u32 v4, v112, v4, s65
	v_and_or_b32 v3, v4, s66, v3
	v_or_b32_e32 v4, s0, v55
	v_mul_u32_u24_e32 v4, 0x1600, v4
	v_lshlrev_b32_e32 v18, 1, v4
	v_lshl_add_u64 v[114:115], v[6:7], 0, v[18:19]
	global_store_dwordx4 v[114:115], v[0:3], off
	v_bfe_u32 v4, v113, 16, 1
	v_add3_u32 v4, v113, v4, s65
	v_bfe_u32 v0, v5, 16, 1
	v_add3_u32 v0, v5, v0, s65
	v_bfe_u32 v1, v9, 16, 1
	v_lshrrev_b32_e32 v0, 16, v0
	v_add3_u32 v1, v9, v1, s65
	v_and_or_b32 v0, v1, s66, v0
	v_bfe_u32 v1, v11, 16, 1
	v_add3_u32 v1, v11, v1, s65
	v_bfe_u32 v2, v13, 16, 1
	v_lshrrev_b32_e32 v1, 16, v1
	v_add3_u32 v2, v13, v2, s65
	v_and_or_b32 v1, v2, s66, v1
	v_bfe_u32 v2, v15, 16, 1
	v_add3_u32 v2, v15, v2, s65
	v_bfe_u32 v3, v89, 16, 1
	v_lshrrev_b32_e32 v2, 16, v2
	v_add3_u32 v3, v89, v3, s65
	v_and_or_b32 v2, v3, s66, v2
	v_bfe_u32 v3, v91, 16, 1
	v_add3_u32 v3, v91, v3, s65
	v_lshrrev_b32_e32 v3, 16, v3
	v_and_or_b32 v3, v4, s66, v3
	v_or_b32_e32 v4, s0, v57
	v_mul_u32_u24_e32 v4, 0x1600, v4
	v_lshlrev_b32_e32 v18, 1, v4
	v_lshl_add_u64 v[4:5], v[6:7], 0, v[18:19]
	global_store_dwordx4 v[4:5], v[0:3], off
	s_waitcnt lgkmcnt(0)

.LBB0_111:
	s_lshl_b32 s24, s1, 1
	s_lshl_b32 s7, s5, 1
	v_or_b32_e32 v75, s24, v54
	s_add_i32 s27, s24, 4
	v_or_b32_e32 v73, s7, v17
	s_add_i32 s26, s7, 4
	s_add_i32 s71, s7, 8
	s_add_i32 s72, s24, 8
	s_add_i32 s73, s7, 12
	s_add_i32 s75, s7, 16
	s_add_i32 s77, s7, 20
	s_add_i32 s79, s7, 24
	s_add_i32 s7, s7, 28
	v_add_u32_e32 v4, s3, v75
	v_or_b32_e32 v79, s27, v54
	s_add_i32 s74, s24, 12
	v_add_u32_e32 v2, s4, v73
	v_or_b32_e32 v77, s26, v17
	v_or_b32_e32 v111, s71, v17
	v_or_b32_e32 v114, s72, v54
	v_or_b32_e32 v115, s73, v17
	v_or_b32_e32 v117, s75, v17
	v_or_b32_e32 v119, s77, v17
	v_or_b32_e32 v121, s79, v17
	v_or_b32_e32 v124, s7, v17
	v_mul_lo_u32 v18, v4, s68
	v_add_u32_e32 v6, s3, v79
	v_mov_b32_e32 v3, v19
	s_add_i32 s76, s24, 16
	v_or_b32_e32 v116, s74, v54
	v_mul_lo_u32 v2, v2, s68
	v_add_u32_e32 v4, s4, v77
	v_add_u32_e32 v125, s3, v114
	v_add_u32_e32 v8, s4, v111
	v_add_u32_e32 v10, s4, v115
	v_add_u32_e32 v12, s4, v117
	v_add_u32_e32 v14, s4, v119
	v_add_u32_e32 v88, s4, v121
	v_add_u32_e32 v112, s4, v124
	v_lshl_add_u64 v[90:91], v[18:19], 2, v[0:1]
	v_mul_lo_u32 v18, v6, s68
	v_mov_b32_e32 v5, v19
	s_add_i32 s78, s24, 20
	v_or_b32_e32 v118, s76, v54
	v_add_u32_e32 v126, s3, v116
	v_lshl_add_u64 v[2:3], v[2:3], 2, v[0:1]
	v_mul_lo_u32 v4, v4, s68
	v_mul_lo_u32 v6, v8, s68
	v_mul_lo_u32 v8, v10, s68
	v_mul_lo_u32 v10, v12, s68
	v_mul_lo_u32 v12, v14, s68
	v_mul_lo_u32 v14, v88, s68
	v_mul_lo_u32 v88, v112, s68
	v_lshl_add_u64 v[112:113], v[18:19], 2, v[0:1]
	v_mul_lo_u32 v18, v125, s68
	s_add_i32 s80, s24, 24
	v_or_b32_e32 v120, s78, v54
	v_add_u32_e32 v127, s3, v118
	v_lshl_add_u64 v[4:5], v[4:5], 2, v[0:1]
	global_load_dword v131, v[90:91], off nt
	global_load_dword v132, v[2:3], off nt
	global_load_dword v133, v[112:113], off nt
	global_load_dword v134, v[4:5], off nt
	v_lshl_add_u64 v[2:3], v[18:19], 2, v[0:1]
	v_mul_lo_u32 v18, v126, s68
	v_mov_b32_e32 v7, v19
	v_mov_b32_e32 v9, v19
	s_add_i32 s24, s24, 28
	v_or_b32_e32 v122, s80, v54
	v_add_u32_e32 v128, s3, v120
	v_lshl_add_u64 v[4:5], v[18:19], 2, v[0:1]
	v_mul_lo_u32 v18, v127, s68
	v_or_b32_e32 v123, s24, v54
	v_add_u32_e32 v129, s3, v122
	v_lshl_add_u64 v[6:7], v[6:7], 2, v[0:1]
	v_lshl_add_u64 v[8:9], v[8:9], 2, v[0:1]
	global_load_dword v126, v[2:3], off nt
	global_load_dword v127, v[6:7], off nt
	global_load_dword v135, v[4:5], off nt
	global_load_dword v136, v[8:9], off nt
	v_lshl_add_u64 v[2:3], v[18:19], 2, v[0:1]
	v_mul_lo_u32 v18, v128, s68
	v_mov_b32_e32 v11, v19
	v_mov_b32_e32 v13, v19
	v_add_u32_e32 v130, s3, v123
	v_lshl_add_u64 v[4:5], v[18:19], 2, v[0:1]
	v_mul_lo_u32 v18, v129, s68
	v_mov_b32_e32 v15, v19
	v_mov_b32_e32 v89, v19
	v_lshl_add_u64 v[10:11], v[10:11], 2, v[0:1]
	v_lshl_add_u64 v[12:13], v[12:13], 2, v[0:1]
	global_load_dword v128, v[2:3], off nt
	global_load_dword v129, v[10:11], off nt
	global_load_dword v137, v[4:5], off nt
	global_load_dword v138, v[12:13], off nt
	v_lshl_add_u64 v[2:3], v[18:19], 2, v[0:1]
	v_mul_lo_u32 v18, v130, s68
	v_lshl_add_u64 v[14:15], v[14:15], 2, v[0:1]
	v_lshl_add_u64 v[88:89], v[88:89], 2, v[0:1]
	v_lshl_add_u64 v[4:5], v[18:19], 2, v[0:1]
	global_load_dword v18, v[2:3], off nt
	global_load_dword v130, v[14:15], off nt
	global_load_dword v139, v[4:5], off nt
	global_load_dword v140, v[88:89], off nt
	s_add_i32 s1, s1, 16
	s_add_i32 s5, s5, 16
	s_add_i32 s6, s6, -16
	v_mad_u64_u32 v[2:3], s[26:27], v75, s49, v[56:57]
	s_cmp_lg_u32 s6, 0
	v_mad_u64_u32 v[4:5], s[26:27], v73, s49, v[56:57]
	v_mad_u64_u32 v[6:7], s[26:27], v79, s49, v[56:57]
	v_mad_u64_u32 v[8:9], s[26:27], v77, s49, v[56:57]
	v_mad_u64_u32 v[10:11], s[26:27], v114, s49, v[56:57]
	v_mad_u64_u32 v[12:13], s[26:27], v111, s49, v[56:57]
	v_mad_u64_u32 v[14:15], s[26:27], v116, s49, v[56:57]
	v_mad_u64_u32 v[88:89], s[26:27], v115, s49, v[56:57]
	v_mad_u64_u32 v[90:91], s[26:27], v118, s49, v[56:57]
	v_mad_u64_u32 v[112:113], s[26:27], v117, s49, v[56:57]
	v_mad_u64_u32 v[114:115], s[26:27], v120, s49, v[56:57]
	v_mad_u64_u32 v[116:117], s[26:27], v119, s49, v[56:57]
	v_mad_u64_u32 v[118:119], s[26:27], v122, s49, v[56:57]
	v_mad_u64_u32 v[120:121], s[26:27], v121, s49, v[56:57]
	v_mad_u64_u32 v[122:123], s[26:27], v123, s49, v[56:57]
	v_mad_u64_u32 v[124:125], s[26:27], v124, s49, v[56:57]
	s_waitcnt vmcnt(0)
	ds_write_b32 v2, v131
	ds_write_b32 v4, v132
	ds_write_b32 v6, v133
	ds_write_b32 v8, v134
	ds_write_b32 v10, v126
	ds_write_b32 v12, v127
	ds_write_b32 v14, v135
	ds_write_b32 v88, v136
	ds_write_b32 v90, v128
	ds_write_b32 v112, v129
	ds_write_b32 v114, v137
	ds_write_b32 v116, v138
	ds_write_b32 v118, v18
	ds_write_b32 v120, v130
	ds_write_b32 v122, v139
	ds_write_b32 v124, v140
	s_cbranch_scc1 .LBB0_111
	s_waitcnt lgkmcnt(0)
	ds_read2_b32 v[4:5], v94 offset1:8
	ds_read2_b32 v[8:9], v94 offset0:33 offset1:41
	ds_read2_b32 v[10:11], v94 offset0:66 offset1:74
	ds_read2_b32 v[12:13], v94 offset0:99 offset1:107
	ds_read2_b32 v[14:15], v94 offset0:132 offset1:140
	s_waitcnt lgkmcnt(0)
	v_bfe_u32 v0, v4, 16, 1
	v_add3_u32 v0, v4, v0, s65
	v_bfe_u32 v1, v8, 16, 1
	v_lshrrev_b32_e32 v0, 16, v0
	v_add3_u32 v1, v8, v1, s65
	ds_read2_b32 v[88:89], v94 offset0:165 offset1:173
	v_and_or_b32 v0, v1, s66, v0
	v_bfe_u32 v1, v10, 16, 1
	v_add3_u32 v1, v10, v1, s65
	v_bfe_u32 v2, v12, 16, 1
	ds_read2_b32 v[90:91], v94 offset0:198 offset1:206
	v_lshrrev_b32_e32 v1, 16, v1
	v_add3_u32 v2, v12, v2, s65
	ds_read2_b32 v[112:113], v94 offset0:231 offset1:239
	v_and_or_b32 v1, v2, s66, v1
	v_bfe_u32 v2, v14, 16, 1
	v_add3_u32 v2, v14, v2, s65
	s_waitcnt lgkmcnt(2)
	v_bfe_u32 v3, v88, 16, 1
	s_add_u32 s1, s44, s2
	v_lshrrev_b32_e32 v2, 16, v2
	v_add3_u32 v3, v88, v3, s65
	s_addc_u32 s4, s45, 0
	s_and_b32 s2, 0xffff, s3
	v_and_or_b32 v2, v3, s66, v2
	s_waitcnt lgkmcnt(1)
	v_bfe_u32 v3, v90, 16, 1
	s_lshl_b32 s2, s2, 1
	v_add3_u32 v3, v90, v3, s65
	s_waitcnt lgkmcnt(0)
	v_bfe_u32 v4, v112, 16, 1
	s_add_u32 s2, s1, s2
	v_lshrrev_b32_e32 v3, 16, v3
	v_add3_u32 v4, v112, v4, s65
	s_addc_u32 s3, s4, 0
	v_lshlrev_b32_e32 v18, 1, v24
	v_and_or_b32 v3, v4, s66, v3
	v_or_b32_e32 v4, s0, v25
	v_lshl_add_u64 v[6:7], s[2:3], 0, v[18:19]
	v_lshlrev_b32_e32 v18, 12, v4
	v_lshl_add_u64 v[114:115], v[6:7], 0, v[18:19]
	global_store_dwordx4 v[114:115], v[0:3], off
	v_bfe_u32 v4, v113, 16, 1
	v_or_b32_e32 v8, s0, v33
	v_bfe_u32 v0, v5, 16, 1
	v_add3_u32 v0, v5, v0, s65
	v_bfe_u32 v1, v9, 16, 1
	v_lshrrev_b32_e32 v0, 16, v0
	v_add3_u32 v1, v9, v1, s65
	v_and_or_b32 v0, v1, s66, v0
	v_bfe_u32 v1, v11, 16, 1
	v_add3_u32 v1, v11, v1, s65
	v_bfe_u32 v2, v13, 16, 1
	v_lshrrev_b32_e32 v1, 16, v1
	v_add3_u32 v2, v13, v2, s65
	v_and_or_b32 v1, v2, s66, v1
	v_bfe_u32 v2, v15, 16, 1
	v_add3_u32 v2, v15, v2, s65
	v_bfe_u32 v3, v89, 16, 1
	v_lshrrev_b32_e32 v2, 16, v2
	v_add3_u32 v3, v89, v3, s65
	v_and_or_b32 v2, v3, s66, v2
	v_bfe_u32 v3, v91, 16, 1
	v_add3_u32 v3, v91, v3, s65
	v_lshrrev_b32_e32 v3, 16, v3
	v_add3_u32 v4, v113, v4, s65
	v_lshlrev_b32_e32 v18, 12, v8
	v_and_or_b32 v3, v4, s66, v3
	ds_read2_b32 v[4:5], v94 offset0:16 offset1:24
	v_lshl_add_u64 v[8:9], v[6:7], 0, v[18:19]
	global_store_dwordx4 v[8:9], v[0:3], off
	ds_read2_b32 v[8:9], v94 offset0:49 offset1:57
	ds_read2_b32 v[10:11], v94 offset0:82 offset1:90
	ds_read2_b32 v[12:13], v94 offset0:115 offset1:123
	s_waitcnt lgkmcnt(3)
	v_bfe_u32 v0, v4, 16, 1
	v_add3_u32 v0, v4, v0, s65
	s_waitcnt lgkmcnt(2)
	v_bfe_u32 v1, v8, 16, 1
	ds_read2_b32 v[14:15], v94 offset0:148 offset1:156
	v_lshrrev_b32_e32 v0, 16, v0
	v_add3_u32 v1, v8, v1, s65
	ds_read2_b32 v[88:89], v94 offset0:181 offset1:189
	v_and_or_b32 v0, v1, s66, v0
	s_waitcnt lgkmcnt(3)
	v_bfe_u32 v1, v10, 16, 1
	v_add3_u32 v1, v10, v1, s65
	s_waitcnt lgkmcnt(2)
	v_bfe_u32 v2, v12, 16, 1
	ds_read2_b32 v[90:91], v94 offset0:214 offset1:222
	v_lshrrev_b32_e32 v1, 16, v1
	v_add3_u32 v2, v12, v2, s65
	ds_read2_b32 v[112:113], v94 offset0:247 offset1:255
	v_and_or_b32 v1, v2, s66, v1
	s_waitcnt lgkmcnt(3)
	v_bfe_u32 v2, v14, 16, 1
	v_add3_u32 v2, v14, v2, s65
	s_waitcnt lgkmcnt(2)
	v_bfe_u32 v3, v88, 16, 1
	v_lshrrev_b32_e32 v2, 16, v2
	v_add3_u32 v3, v88, v3, s65
	v_and_or_b32 v2, v3, s66, v2
	s_waitcnt lgkmcnt(1)
	v_bfe_u32 v3, v90, 16, 1
	v_add3_u32 v3, v90, v3, s65
	s_waitcnt lgkmcnt(0)
	v_bfe_u32 v4, v112, 16, 1
	v_lshrrev_b32_e32 v3, 16, v3
	v_add3_u32 v4, v112, v4, s65
	v_and_or_b32 v3, v4, s66, v3
	v_or_b32_e32 v4, s0, v55
	v_lshlrev_b32_e32 v18, 12, v4
	v_lshl_add_u64 v[114:115], v[6:7], 0, v[18:19]
	global_store_dwordx4 v[114:115], v[0:3], off
	v_bfe_u32 v4, v113, 16, 1
	v_add3_u32 v4, v113, v4, s65
	v_bfe_u32 v0, v5, 16, 1
	v_add3_u32 v0, v5, v0, s65
	v_bfe_u32 v1, v9, 16, 1
	v_lshrrev_b32_e32 v0, 16, v0
	v_add3_u32 v1, v9, v1, s65
	v_and_or_b32 v0, v1, s66, v0
	v_bfe_u32 v1, v11, 16, 1
	v_add3_u32 v1, v11, v1, s65
	v_bfe_u32 v2, v13, 16, 1
	v_lshrrev_b32_e32 v1, 16, v1
	v_add3_u32 v2, v13, v2, s65
	v_and_or_b32 v1, v2, s66, v1
	v_bfe_u32 v2, v15, 16, 1
	v_add3_u32 v2, v15, v2, s65
	v_bfe_u32 v3, v89, 16, 1
	v_lshrrev_b32_e32 v2, 16, v2
	v_add3_u32 v3, v89, v3, s65
	v_and_or_b32 v2, v3, s66, v2
	v_bfe_u32 v3, v91, 16, 1
	v_add3_u32 v3, v91, v3, s65
	v_lshrrev_b32_e32 v3, 16, v3
	v_and_or_b32 v3, v4, s66, v3
	v_or_b32_e32 v4, s0, v57
	v_lshlrev_b32_e32 v18, 12, v4
	v_lshl_add_u64 v[4:5], v[6:7], 0, v[18:19]
	global_store_dwordx4 v[4:5], v[0:3], off
	s_waitcnt lgkmcnt(0)

.LBB0_117:
	s_mov_b32 s73, 0
	s_mov_b32 s74, 0x20000
	s_mov_b32 s75, 0
	v_mov_b64_e32 v[228:229], v[88:89]
	s_mov_b32 s72, 0x4000
	v_lshl_add_u64 v[230:231], v[88:89], 0, s[72:73]
	s_mov_b32 s72, 0x8000
	v_lshl_add_u64 v[232:233], v[88:89], 0, s[72:73]
	s_mov_b32 s72, 0xc000
	v_lshl_add_u64 v[234:235], v[88:89], 0, s[72:73]
	s_mov_b32 s72, 0x10000
	v_lshl_add_u64 v[236:237], v[88:89], 0, s[72:73]
	s_mov_b32 s72, 0x14000
	v_lshl_add_u64 v[238:239], v[88:89], 0, s[72:73]
	s_mov_b32 s72, 0x18000
	v_lshl_add_u64 v[240:241], v[88:89], 0, s[72:73]
	s_mov_b32 s72, 0x1c000
	v_lshl_add_u64 v[242:243], v[88:89], 0, s[72:73]
	global_load_dwordx4 v[164:167], v[228:229], off nt
	v_lshl_add_u64 v[228:229], v[228:229], 0, s[74:75]
	global_load_dwordx4 v[168:171], v[230:231], off nt
	v_lshl_add_u64 v[230:231], v[230:231], 0, s[74:75]
	global_load_dwordx4 v[172:175], v[232:233], off nt
	v_lshl_add_u64 v[232:233], v[232:233], 0, s[74:75]
	global_load_dwordx4 v[176:179], v[234:235], off nt
	v_lshl_add_u64 v[234:235], v[234:235], 0, s[74:75]
	global_load_dwordx4 v[180:183], v[236:237], off nt
	v_lshl_add_u64 v[236:237], v[236:237], 0, s[74:75]
	global_load_dwordx4 v[184:187], v[238:239], off nt
	v_lshl_add_u64 v[238:239], v[238:239], 0, s[74:75]
	global_load_dwordx4 v[188:191], v[240:241], off nt
	v_lshl_add_u64 v[240:241], v[240:241], 0, s[74:75]
	global_load_dwordx4 v[192:195], v[242:243], off nt
	v_lshl_add_u64 v[242:243], v[242:243], 0, s[74:75]
	s_mov_b32 s76, 31
.Lgemv_kv_loop:
	v_mov_b32_e32 v244, s2
	ds_read_b128 v[196:199], v244
	ds_read_b128 v[200:203], v244 offset:16
	ds_read_b128 v[204:207], v244 offset:1024
	ds_read_b128 v[208:211], v244 offset:1040
	ds_read_b128 v[212:215], v244 offset:2048
	ds_read_b128 v[216:219], v244 offset:2064
	ds_read_b128 v[220:223], v244 offset:3072
	ds_read_b128 v[224:227], v244 offset:3088
	s_add_i32 s2, s2, 32
	s_waitcnt lgkmcnt(0)
	s_waitcnt vmcnt(7)
	v_pk_fma_f32 v[8:9], v[164:165], v[196:197], v[8:9] op_sel_hi:[1,0,1]
	v_pk_fma_f32 v[10:11], v[166:167], v[196:197], v[10:11] op_sel_hi:[1,0,1]
	v_pk_fma_f32 v[12:13], v[164:165], v[204:205], v[12:13] op_sel_hi:[1,0,1]
	v_pk_fma_f32 v[14:15], v[166:167], v[204:205], v[14:15] op_sel_hi:[1,0,1]
	v_pk_fma_f32 v[4:5], v[164:165], v[212:213], v[4:5] op_sel_hi:[1,0,1]
	v_pk_fma_f32 v[6:7], v[166:167], v[212:213], v[6:7] op_sel_hi:[1,0,1]
	v_pk_fma_f32 v[0:1], v[164:165], v[220:221], v[0:1] op_sel_hi:[1,0,1]
	v_pk_fma_f32 v[2:3], v[166:167], v[220:221], v[2:3] op_sel_hi:[1,0,1]
	global_load_dwordx4 v[164:167], v[228:229], off nt
	v_lshl_add_u64 v[228:229], v[228:229], 0, s[74:75]
	s_waitcnt vmcnt(7)
	v_pk_fma_f32 v[8:9], v[168:169], v[196:197], v[8:9] op_sel:[0,1,0]
	v_pk_fma_f32 v[10:11], v[170:171], v[196:197], v[10:11] op_sel:[0,1,0]
	v_pk_fma_f32 v[12:13], v[168:169], v[204:205], v[12:13] op_sel:[0,1,0]
	v_pk_fma_f32 v[14:15], v[170:171], v[204:205], v[14:15] op_sel:[0,1,0]
	v_pk_fma_f32 v[4:5], v[168:169], v[212:213], v[4:5] op_sel:[0,1,0]
	v_pk_fma_f32 v[6:7], v[170:171], v[212:213], v[6:7] op_sel:[0,1,0]
	v_pk_fma_f32 v[0:1], v[168:169], v[220:221], v[0:1] op_sel:[0,1,0]
	v_pk_fma_f32 v[2:3], v[170:171], v[220:221], v[2:3] op_sel:[0,1,0]
	global_load_dwordx4 v[168:171], v[230:231], off nt
	v_lshl_add_u64 v[230:231], v[230:231], 0, s[74:75]
	s_waitcnt vmcnt(7)
	v_pk_fma_f32 v[8:9], v[172:173], v[198:199], v[8:9] op_sel_hi:[1,0,1]
	v_pk_fma_f32 v[10:11], v[174:175], v[198:199], v[10:11] op_sel_hi:[1,0,1]
	v_pk_fma_f32 v[12:13], v[172:173], v[206:207], v[12:13] op_sel_hi:[1,0,1]
	v_pk_fma_f32 v[14:15], v[174:175], v[206:207], v[14:15] op_sel_hi:[1,0,1]
	v_pk_fma_f32 v[4:5], v[172:173], v[214:215], v[4:5] op_sel_hi:[1,0,1]
	v_pk_fma_f32 v[6:7], v[174:175], v[214:215], v[6:7] op_sel_hi:[1,0,1]
	v_pk_fma_f32 v[0:1], v[172:173], v[222:223], v[0:1] op_sel_hi:[1,0,1]
	v_pk_fma_f32 v[2:3], v[174:175], v[222:223], v[2:3] op_sel_hi:[1,0,1]
	global_load_dwordx4 v[172:175], v[232:233], off nt
	v_lshl_add_u64 v[232:233], v[232:233], 0, s[74:75]
	s_waitcnt vmcnt(7)
	v_pk_fma_f32 v[8:9], v[176:177], v[198:199], v[8:9] op_sel:[0,1,0]
	v_pk_fma_f32 v[10:11], v[178:179], v[198:199], v[10:11] op_sel:[0,1,0]
	v_pk_fma_f32 v[12:13], v[176:177], v[206:207], v[12:13] op_sel:[0,1,0]
	v_pk_fma_f32 v[14:15], v[178:179], v[206:207], v[14:15] op_sel:[0,1,0]
	v_pk_fma_f32 v[4:5], v[176:177], v[214:215], v[4:5] op_sel:[0,1,0]
	v_pk_fma_f32 v[6:7], v[178:179], v[214:215], v[6:7] op_sel:[0,1,0]
	v_pk_fma_f32 v[0:1], v[176:177], v[222:223], v[0:1] op_sel:[0,1,0]
	v_pk_fma_f32 v[2:3], v[178:179], v[222:223], v[2:3] op_sel:[0,1,0]
	global_load_dwordx4 v[176:179], v[234:235], off nt
	v_lshl_add_u64 v[234:235], v[234:235], 0, s[74:75]
	s_waitcnt vmcnt(7)
	v_pk_fma_f32 v[8:9], v[180:181], v[200:201], v[8:9] op_sel_hi:[1,0,1]
	v_pk_fma_f32 v[10:11], v[182:183], v[200:201], v[10:11] op_sel_hi:[1,0,1]
	v_pk_fma_f32 v[12:13], v[180:181], v[208:209], v[12:13] op_sel_hi:[1,0,1]
	v_pk_fma_f32 v[14:15], v[182:183], v[208:209], v[14:15] op_sel_hi:[1,0,1]
	v_pk_fma_f32 v[4:5], v[180:181], v[216:217], v[4:5] op_sel_hi:[1,0,1]
	v_pk_fma_f32 v[6:7], v[182:183], v[216:217], v[6:7] op_sel_hi:[1,0,1]
	v_pk_fma_f32 v[0:1], v[180:181], v[224:225], v[0:1] op_sel_hi:[1,0,1]
	v_pk_fma_f32 v[2:3], v[182:183], v[224:225], v[2:3] op_sel_hi:[1,0,1]
	global_load_dwordx4 v[180:183], v[236:237], off nt
	v_lshl_add_u64 v[236:237], v[236:237], 0, s[74:75]
	s_waitcnt vmcnt(7)
	v_pk_fma_f32 v[8:9], v[184:185], v[200:201], v[8:9] op_sel:[0,1,0]
	v_pk_fma_f32 v[10:11], v[186:187], v[200:201], v[10:11] op_sel:[0,1,0]
	v_pk_fma_f32 v[12:13], v[184:185], v[208:209], v[12:13] op_sel:[0,1,0]
	v_pk_fma_f32 v[14:15], v[186:187], v[208:209], v[14:15] op_sel:[0,1,0]
	v_pk_fma_f32 v[4:5], v[184:185], v[216:217], v[4:5] op_sel:[0,1,0]
	v_pk_fma_f32 v[6:7], v[186:187], v[216:217], v[6:7] op_sel:[0,1,0]
	v_pk_fma_f32 v[0:1], v[184:185], v[224:225], v[0:1] op_sel:[0,1,0]
	v_pk_fma_f32 v[2:3], v[186:187], v[224:225], v[2:3] op_sel:[0,1,0]
	global_load_dwordx4 v[184:187], v[238:239], off nt
	v_lshl_add_u64 v[238:239], v[238:239], 0, s[74:75]
	s_waitcnt vmcnt(7)
	v_pk_fma_f32 v[8:9], v[188:189], v[202:203], v[8:9] op_sel_hi:[1,0,1]
	v_pk_fma_f32 v[10:11], v[190:191], v[202:203], v[10:11] op_sel_hi:[1,0,1]
	v_pk_fma_f32 v[12:13], v[188:189], v[210:211], v[12:13] op_sel_hi:[1,0,1]
	v_pk_fma_f32 v[14:15], v[190:191], v[210:211], v[14:15] op_sel_hi:[1,0,1]
	v_pk_fma_f32 v[4:5], v[188:189], v[218:219], v[4:5] op_sel_hi:[1,0,1]
	v_pk_fma_f32 v[6:7], v[190:191], v[218:219], v[6:7] op_sel_hi:[1,0,1]
	v_pk_fma_f32 v[0:1], v[188:189], v[226:227], v[0:1] op_sel_hi:[1,0,1]
	v_pk_fma_f32 v[2:3], v[190:191], v[226:227], v[2:3] op_sel_hi:[1,0,1]
	global_load_dwordx4 v[188:191], v[240:241], off nt
	v_lshl_add_u64 v[240:241], v[240:241], 0, s[74:75]
	s_waitcnt vmcnt(7)
	v_pk_fma_f32 v[8:9], v[192:193], v[202:203], v[8:9] op_sel:[0,1,0]
	v_pk_fma_f32 v[10:11], v[194:195], v[202:203], v[10:11] op_sel:[0,1,0]
	v_pk_fma_f32 v[12:13], v[192:193], v[210:211], v[12:13] op_sel:[0,1,0]
	v_pk_fma_f32 v[14:15], v[194:195], v[210:211], v[14:15] op_sel:[0,1,0]
	v_pk_fma_f32 v[4:5], v[192:193], v[218:219], v[4:5] op_sel:[0,1,0]
	v_pk_fma_f32 v[6:7], v[194:195], v[218:219], v[6:7] op_sel:[0,1,0]
	v_pk_fma_f32 v[0:1], v[192:193], v[226:227], v[0:1] op_sel:[0,1,0]
	v_pk_fma_f32 v[2:3], v[194:195], v[226:227], v[2:3] op_sel:[0,1,0]
	global_load_dwordx4 v[192:195], v[242:243], off nt
	v_lshl_add_u64 v[242:243], v[242:243], 0, s[74:75]
	s_add_i32 s76, s76, -1
	s_cmp_eq_u32 s76, 0
	s_cbranch_scc0 .Lgemv_kv_loop
	v_mov_b32_e32 v244, s2
	ds_read_b128 v[196:199], v244
	ds_read_b128 v[200:203], v244 offset:16
	ds_read_b128 v[204:207], v244 offset:1024
	ds_read_b128 v[208:211], v244 offset:1040
	ds_read_b128 v[212:215], v244 offset:2048
	ds_read_b128 v[216:219], v244 offset:2064
	ds_read_b128 v[220:223], v244 offset:3072
	ds_read_b128 v[224:227], v244 offset:3088
	s_waitcnt lgkmcnt(0)
	s_waitcnt vmcnt(7)
	v_pk_fma_f32 v[8:9], v[164:165], v[196:197], v[8:9] op_sel_hi:[1,0,1]
	v_pk_fma_f32 v[10:11], v[166:167], v[196:197], v[10:11] op_sel_hi:[1,0,1]
	v_pk_fma_f32 v[12:13], v[164:165], v[204:205], v[12:13] op_sel_hi:[1,0,1]
	v_pk_fma_f32 v[14:15], v[166:167], v[204:205], v[14:15] op_sel_hi:[1,0,1]
	v_pk_fma_f32 v[4:5], v[164:165], v[212:213], v[4:5] op_sel_hi:[1,0,1]
	v_pk_fma_f32 v[6:7], v[166:167], v[212:213], v[6:7] op_sel_hi:[1,0,1]
	v_pk_fma_f32 v[0:1], v[164:165], v[220:221], v[0:1] op_sel_hi:[1,0,1]
	v_pk_fma_f32 v[2:3], v[166:167], v[220:221], v[2:3] op_sel_hi:[1,0,1]
	s_waitcnt vmcnt(6)
	v_pk_fma_f32 v[8:9], v[168:169], v[196:197], v[8:9] op_sel:[0,1,0]
	v_pk_fma_f32 v[10:11], v[170:171], v[196:197], v[10:11] op_sel:[0,1,0]
	v_pk_fma_f32 v[12:13], v[168:169], v[204:205], v[12:13] op_sel:[0,1,0]
	v_pk_fma_f32 v[14:15], v[170:171], v[204:205], v[14:15] op_sel:[0,1,0]
	v_pk_fma_f32 v[4:5], v[168:169], v[212:213], v[4:5] op_sel:[0,1,0]
	v_pk_fma_f32 v[6:7], v[170:171], v[212:213], v[6:7] op_sel:[0,1,0]
	v_pk_fma_f32 v[0:1], v[168:169], v[220:221], v[0:1] op_sel:[0,1,0]
	v_pk_fma_f32 v[2:3], v[170:171], v[220:221], v[2:3] op_sel:[0,1,0]
	s_waitcnt vmcnt(5)
	v_pk_fma_f32 v[8:9], v[172:173], v[198:199], v[8:9] op_sel_hi:[1,0,1]
	v_pk_fma_f32 v[10:11], v[174:175], v[198:199], v[10:11] op_sel_hi:[1,0,1]
	v_pk_fma_f32 v[12:13], v[172:173], v[206:207], v[12:13] op_sel_hi:[1,0,1]
	v_pk_fma_f32 v[14:15], v[174:175], v[206:207], v[14:15] op_sel_hi:[1,0,1]
	v_pk_fma_f32 v[4:5], v[172:173], v[214:215], v[4:5] op_sel_hi:[1,0,1]
	v_pk_fma_f32 v[6:7], v[174:175], v[214:215], v[6:7] op_sel_hi:[1,0,1]
	v_pk_fma_f32 v[0:1], v[172:173], v[222:223], v[0:1] op_sel_hi:[1,0,1]
	v_pk_fma_f32 v[2:3], v[174:175], v[222:223], v[2:3] op_sel_hi:[1,0,1]
	s_waitcnt vmcnt(4)
	v_pk_fma_f32 v[8:9], v[176:177], v[198:199], v[8:9] op_sel:[0,1,0]
	v_pk_fma_f32 v[10:11], v[178:179], v[198:199], v[10:11] op_sel:[0,1,0]
	v_pk_fma_f32 v[12:13], v[176:177], v[206:207], v[12:13] op_sel:[0,1,0]
	v_pk_fma_f32 v[14:15], v[178:179], v[206:207], v[14:15] op_sel:[0,1,0]
	v_pk_fma_f32 v[4:5], v[176:177], v[214:215], v[4:5] op_sel:[0,1,0]
	v_pk_fma_f32 v[6:7], v[178:179], v[214:215], v[6:7] op_sel:[0,1,0]
	v_pk_fma_f32 v[0:1], v[176:177], v[222:223], v[0:1] op_sel:[0,1,0]
	v_pk_fma_f32 v[2:3], v[178:179], v[222:223], v[2:3] op_sel:[0,1,0]
	s_waitcnt vmcnt(3)
	v_pk_fma_f32 v[8:9], v[180:181], v[200:201], v[8:9] op_sel_hi:[1,0,1]
	v_pk_fma_f32 v[10:11], v[182:183], v[200:201], v[10:11] op_sel_hi:[1,0,1]
	v_pk_fma_f32 v[12:13], v[180:181], v[208:209], v[12:13] op_sel_hi:[1,0,1]
	v_pk_fma_f32 v[14:15], v[182:183], v[208:209], v[14:15] op_sel_hi:[1,0,1]
	v_pk_fma_f32 v[4:5], v[180:181], v[216:217], v[4:5] op_sel_hi:[1,0,1]
	v_pk_fma_f32 v[6:7], v[182:183], v[216:217], v[6:7] op_sel_hi:[1,0,1]
	v_pk_fma_f32 v[0:1], v[180:181], v[224:225], v[0:1] op_sel_hi:[1,0,1]
	v_pk_fma_f32 v[2:3], v[182:183], v[224:225], v[2:3] op_sel_hi:[1,0,1]
	s_waitcnt vmcnt(2)
	v_pk_fma_f32 v[8:9], v[184:185], v[200:201], v[8:9] op_sel:[0,1,0]
	v_pk_fma_f32 v[10:11], v[186:187], v[200:201], v[10:11] op_sel:[0,1,0]
	v_pk_fma_f32 v[12:13], v[184:185], v[208:209], v[12:13] op_sel:[0,1,0]
	v_pk_fma_f32 v[14:15], v[186:187], v[208:209], v[14:15] op_sel:[0,1,0]
	v_pk_fma_f32 v[4:5], v[184:185], v[216:217], v[4:5] op_sel:[0,1,0]
	v_pk_fma_f32 v[6:7], v[186:187], v[216:217], v[6:7] op_sel:[0,1,0]
	v_pk_fma_f32 v[0:1], v[184:185], v[224:225], v[0:1] op_sel:[0,1,0]
	v_pk_fma_f32 v[2:3], v[186:187], v[224:225], v[2:3] op_sel:[0,1,0]
	s_waitcnt vmcnt(1)
	v_pk_fma_f32 v[8:9], v[188:189], v[202:203], v[8:9] op_sel_hi:[1,0,1]
	v_pk_fma_f32 v[10:11], v[190:191], v[202:203], v[10:11] op_sel_hi:[1,0,1]
	v_pk_fma_f32 v[12:13], v[188:189], v[210:211], v[12:13] op_sel_hi:[1,0,1]
	v_pk_fma_f32 v[14:15], v[190:191], v[210:211], v[14:15] op_sel_hi:[1,0,1]
	v_pk_fma_f32 v[4:5], v[188:189], v[218:219], v[4:5] op_sel_hi:[1,0,1]
	v_pk_fma_f32 v[6:7], v[190:191], v[218:219], v[6:7] op_sel_hi:[1,0,1]
	v_pk_fma_f32 v[0:1], v[188:189], v[226:227], v[0:1] op_sel_hi:[1,0,1]
	v_pk_fma_f32 v[2:3], v[190:191], v[226:227], v[2:3] op_sel_hi:[1,0,1]
	s_waitcnt vmcnt(0)
	v_pk_fma_f32 v[8:9], v[192:193], v[202:203], v[8:9] op_sel:[0,1,0]
	v_pk_fma_f32 v[10:11], v[194:195], v[202:203], v[10:11] op_sel:[0,1,0]
	v_pk_fma_f32 v[12:13], v[192:193], v[210:211], v[12:13] op_sel:[0,1,0]
	v_pk_fma_f32 v[14:15], v[194:195], v[210:211], v[14:15] op_sel:[0,1,0]
	v_pk_fma_f32 v[4:5], v[192:193], v[218:219], v[4:5] op_sel:[0,1,0]
	v_pk_fma_f32 v[6:7], v[194:195], v[218:219], v[6:7] op_sel:[0,1,0]
	v_pk_fma_f32 v[0:1], v[192:193], v[226:227], v[0:1] op_sel:[0,1,0]
	v_pk_fma_f32 v[2:3], v[194:195], v[226:227], v[2:3] op_sel:[0,1,0]
	s_and_b64 vcc, exec, s[34:35]
	s_cbranch_vccz .LBB0_120
	v_lshl_add_u64 v[88:89], s[24:25], 2, v[80:81]
	global_load_dwordx4 v[88:91], v[88:89], off
	s_waitcnt vmcnt(0)
	v_pk_add_f32 v[10:11], v[10:11], v[90:91]
	v_pk_add_f32 v[8:9], v[8:9], v[88:89]
	v_pk_add_f32 v[14:15], v[14:15], v[90:91]
	v_pk_add_f32 v[12:13], v[12:13], v[88:89]
	v_pk_add_f32 v[6:7], v[6:7], v[90:91]
	v_pk_add_f32 v[4:5], v[4:5], v[88:89]
	v_pk_add_f32 v[2:3], v[2:3], v[90:91]
	v_pk_add_f32 v[0:1], v[0:1], v[88:89]

.LBB0_123:
	s_mov_b32 s73, 0
	s_mov_b32 s74, 0x60000
	s_mov_b32 s75, 0
	v_mov_b64_e32 v[228:229], v[88:89]
	s_mov_b32 s72, 0xc000
	v_lshl_add_u64 v[230:231], v[88:89], 0, s[72:73]
	s_mov_b32 s72, 0x18000
	v_lshl_add_u64 v[232:233], v[88:89], 0, s[72:73]
	s_mov_b32 s72, 0x24000
	v_lshl_add_u64 v[234:235], v[88:89], 0, s[72:73]
	s_mov_b32 s72, 0x30000
	v_lshl_add_u64 v[236:237], v[88:89], 0, s[72:73]
	s_mov_b32 s72, 0x3c000
	v_lshl_add_u64 v[238:239], v[88:89], 0, s[72:73]
	s_mov_b32 s72, 0x48000
	v_lshl_add_u64 v[240:241], v[88:89], 0, s[72:73]
	s_mov_b32 s72, 0x54000
	v_lshl_add_u64 v[242:243], v[88:89], 0, s[72:73]
	global_load_dwordx4 v[164:167], v[228:229], off nt
	v_lshl_add_u64 v[228:229], v[228:229], 0, s[74:75]
	global_load_dwordx4 v[168:171], v[230:231], off nt
	v_lshl_add_u64 v[230:231], v[230:231], 0, s[74:75]
	global_load_dwordx4 v[172:175], v[232:233], off nt
	v_lshl_add_u64 v[232:233], v[232:233], 0, s[74:75]
	global_load_dwordx4 v[176:179], v[234:235], off nt
	v_lshl_add_u64 v[234:235], v[234:235], 0, s[74:75]
	global_load_dwordx4 v[180:183], v[236:237], off nt
	v_lshl_add_u64 v[236:237], v[236:237], 0, s[74:75]
	global_load_dwordx4 v[184:187], v[238:239], off nt
	v_lshl_add_u64 v[238:239], v[238:239], 0, s[74:75]
	global_load_dwordx4 v[188:191], v[240:241], off nt
	v_lshl_add_u64 v[240:241], v[240:241], 0, s[74:75]
	global_load_dwordx4 v[192:195], v[242:243], off nt
	v_lshl_add_u64 v[242:243], v[242:243], 0, s[74:75]
	s_mov_b32 s76, 31
.Lgemv_mod_loop:
	v_mov_b32_e32 v244, s4
	ds_read_b128 v[196:199], v244
	ds_read_b128 v[200:203], v244 offset:16
	ds_read_b128 v[204:207], v244 offset:1024
	ds_read_b128 v[208:211], v244 offset:1040
	ds_read_b128 v[212:215], v244 offset:2048
	ds_read_b128 v[216:219], v244 offset:2064
	ds_read_b128 v[220:223], v244 offset:3072
	ds_read_b128 v[224:227], v244 offset:3088
	s_add_i32 s4, s4, 32
	s_waitcnt lgkmcnt(0)
	s_waitcnt vmcnt(7)
	v_pk_fma_f32 v[8:9], v[164:165], v[196:197], v[8:9] op_sel_hi:[1,0,1]
	v_pk_fma_f32 v[10:11], v[166:167], v[196:197], v[10:11] op_sel_hi:[1,0,1]
	v_pk_fma_f32 v[12:13], v[164:165], v[204:205], v[12:13] op_sel_hi:[1,0,1]
	v_pk_fma_f32 v[14:15], v[166:167], v[204:205], v[14:15] op_sel_hi:[1,0,1]
	v_pk_fma_f32 v[4:5], v[164:165], v[212:213], v[4:5] op_sel_hi:[1,0,1]
	v_pk_fma_f32 v[6:7], v[166:167], v[212:213], v[6:7] op_sel_hi:[1,0,1]
	v_pk_fma_f32 v[0:1], v[164:165], v[220:221], v[0:1] op_sel_hi:[1,0,1]
	v_pk_fma_f32 v[2:3], v[166:167], v[220:221], v[2:3] op_sel_hi:[1,0,1]
	global_load_dwordx4 v[164:167], v[228:229], off nt
	v_lshl_add_u64 v[228:229], v[228:229], 0, s[74:75]
	s_waitcnt vmcnt(7)
	v_pk_fma_f32 v[8:9], v[168:169], v[196:197], v[8:9] op_sel:[0,1,0]
	v_pk_fma_f32 v[10:11], v[170:171], v[196:197], v[10:11] op_sel:[0,1,0]
	v_pk_fma_f32 v[12:13], v[168:169], v[204:205], v[12:13] op_sel:[0,1,0]
	v_pk_fma_f32 v[14:15], v[170:171], v[204:205], v[14:15] op_sel:[0,1,0]
	v_pk_fma_f32 v[4:5], v[168:169], v[212:213], v[4:5] op_sel:[0,1,0]
	v_pk_fma_f32 v[6:7], v[170:171], v[212:213], v[6:7] op_sel:[0,1,0]
	v_pk_fma_f32 v[0:1], v[168:169], v[220:221], v[0:1] op_sel:[0,1,0]
	v_pk_fma_f32 v[2:3], v[170:171], v[220:221], v[2:3] op_sel:[0,1,0]
	global_load_dwordx4 v[168:171], v[230:231], off nt
	v_lshl_add_u64 v[230:231], v[230:231], 0, s[74:75]
	s_waitcnt vmcnt(7)
	v_pk_fma_f32 v[8:9], v[172:173], v[198:199], v[8:9] op_sel_hi:[1,0,1]
	v_pk_fma_f32 v[10:11], v[174:175], v[198:199], v[10:11] op_sel_hi:[1,0,1]
	v_pk_fma_f32 v[12:13], v[172:173], v[206:207], v[12:13] op_sel_hi:[1,0,1]
	v_pk_fma_f32 v[14:15], v[174:175], v[206:207], v[14:15] op_sel_hi:[1,0,1]
	v_pk_fma_f32 v[4:5], v[172:173], v[214:215], v[4:5] op_sel_hi:[1,0,1]
	v_pk_fma_f32 v[6:7], v[174:175], v[214:215], v[6:7] op_sel_hi:[1,0,1]
	v_pk_fma_f32 v[0:1], v[172:173], v[222:223], v[0:1] op_sel_hi:[1,0,1]
	v_pk_fma_f32 v[2:3], v[174:175], v[222:223], v[2:3] op_sel_hi:[1,0,1]
	global_load_dwordx4 v[172:175], v[232:233], off nt
	v_lshl_add_u64 v[232:233], v[232:233], 0, s[74:75]
	s_waitcnt vmcnt(7)
	v_pk_fma_f32 v[8:9], v[176:177], v[198:199], v[8:9] op_sel:[0,1,0]
	v_pk_fma_f32 v[10:11], v[178:179], v[198:199], v[10:11] op_sel:[0,1,0]
	v_pk_fma_f32 v[12:13], v[176:177], v[206:207], v[12:13] op_sel:[0,1,0]
	v_pk_fma_f32 v[14:15], v[178:179], v[206:207], v[14:15] op_sel:[0,1,0]
	v_pk_fma_f32 v[4:5], v[176:177], v[214:215], v[4:5] op_sel:[0,1,0]
	v_pk_fma_f32 v[6:7], v[178:179], v[214:215], v[6:7] op_sel:[0,1,0]
	v_pk_fma_f32 v[0:1], v[176:177], v[222:223], v[0:1] op_sel:[0,1,0]
	v_pk_fma_f32 v[2:3], v[178:179], v[222:223], v[2:3] op_sel:[0,1,0]
	global_load_dwordx4 v[176:179], v[234:235], off nt
	v_lshl_add_u64 v[234:235], v[234:235], 0, s[74:75]
	s_waitcnt vmcnt(7)
	v_pk_fma_f32 v[8:9], v[180:181], v[200:201], v[8:9] op_sel_hi:[1,0,1]
	v_pk_fma_f32 v[10:11], v[182:183], v[200:201], v[10:11] op_sel_hi:[1,0,1]
	v_pk_fma_f32 v[12:13], v[180:181], v[208:209], v[12:13] op_sel_hi:[1,0,1]
	v_pk_fma_f32 v[14:15], v[182:183], v[208:209], v[14:15] op_sel_hi:[1,0,1]
	v_pk_fma_f32 v[4:5], v[180:181], v[216:217], v[4:5] op_sel_hi:[1,0,1]
	v_pk_fma_f32 v[6:7], v[182:183], v[216:217], v[6:7] op_sel_hi:[1,0,1]
	v_pk_fma_f32 v[0:1], v[180:181], v[224:225], v[0:1] op_sel_hi:[1,0,1]
	v_pk_fma_f32 v[2:3], v[182:183], v[224:225], v[2:3] op_sel_hi:[1,0,1]
	global_load_dwordx4 v[180:183], v[236:237], off nt
	v_lshl_add_u64 v[236:237], v[236:237], 0, s[74:75]
	s_waitcnt vmcnt(7)
	v_pk_fma_f32 v[8:9], v[184:185], v[200:201], v[8:9] op_sel:[0,1,0]
	v_pk_fma_f32 v[10:11], v[186:187], v[200:201], v[10:11] op_sel:[0,1,0]
	v_pk_fma_f32 v[12:13], v[184:185], v[208:209], v[12:13] op_sel:[0,1,0]
	v_pk_fma_f32 v[14:15], v[186:187], v[208:209], v[14:15] op_sel:[0,1,0]
	v_pk_fma_f32 v[4:5], v[184:185], v[216:217], v[4:5] op_sel:[0,1,0]
	v_pk_fma_f32 v[6:7], v[186:187], v[216:217], v[6:7] op_sel:[0,1,0]
	v_pk_fma_f32 v[0:1], v[184:185], v[224:225], v[0:1] op_sel:[0,1,0]
	v_pk_fma_f32 v[2:3], v[186:187], v[224:225], v[2:3] op_sel:[0,1,0]
	global_load_dwordx4 v[184:187], v[238:239], off nt
	v_lshl_add_u64 v[238:239], v[238:239], 0, s[74:75]
	s_waitcnt vmcnt(7)
	v_pk_fma_f32 v[8:9], v[188:189], v[202:203], v[8:9] op_sel_hi:[1,0,1]
	v_pk_fma_f32 v[10:11], v[190:191], v[202:203], v[10:11] op_sel_hi:[1,0,1]
	v_pk_fma_f32 v[12:13], v[188:189], v[210:211], v[12:13] op_sel_hi:[1,0,1]
	v_pk_fma_f32 v[14:15], v[190:191], v[210:211], v[14:15] op_sel_hi:[1,0,1]
	v_pk_fma_f32 v[4:5], v[188:189], v[218:219], v[4:5] op_sel_hi:[1,0,1]
	v_pk_fma_f32 v[6:7], v[190:191], v[218:219], v[6:7] op_sel_hi:[1,0,1]
	v_pk_fma_f32 v[0:1], v[188:189], v[226:227], v[0:1] op_sel_hi:[1,0,1]
	v_pk_fma_f32 v[2:3], v[190:191], v[226:227], v[2:3] op_sel_hi:[1,0,1]
	global_load_dwordx4 v[188:191], v[240:241], off nt
	v_lshl_add_u64 v[240:241], v[240:241], 0, s[74:75]
	s_waitcnt vmcnt(7)
	v_pk_fma_f32 v[8:9], v[192:193], v[202:203], v[8:9] op_sel:[0,1,0]
	v_pk_fma_f32 v[10:11], v[194:195], v[202:203], v[10:11] op_sel:[0,1,0]
	v_pk_fma_f32 v[12:13], v[192:193], v[210:211], v[12:13] op_sel:[0,1,0]
	v_pk_fma_f32 v[14:15], v[194:195], v[210:211], v[14:15] op_sel:[0,1,0]
	v_pk_fma_f32 v[4:5], v[192:193], v[218:219], v[4:5] op_sel:[0,1,0]
	v_pk_fma_f32 v[6:7], v[194:195], v[218:219], v[6:7] op_sel:[0,1,0]
	v_pk_fma_f32 v[0:1], v[192:193], v[226:227], v[0:1] op_sel:[0,1,0]
	v_pk_fma_f32 v[2:3], v[194:195], v[226:227], v[2:3] op_sel:[0,1,0]
	global_load_dwordx4 v[192:195], v[242:243], off nt
	v_lshl_add_u64 v[242:243], v[242:243], 0, s[74:75]
	s_add_i32 s76, s76, -1
	s_cmp_eq_u32 s76, 0
	s_cbranch_scc0 .Lgemv_mod_loop
	v_mov_b32_e32 v244, s4
	ds_read_b128 v[196:199], v244
	ds_read_b128 v[200:203], v244 offset:16
	ds_read_b128 v[204:207], v244 offset:1024
	ds_read_b128 v[208:211], v244 offset:1040
	ds_read_b128 v[212:215], v244 offset:2048
	ds_read_b128 v[216:219], v244 offset:2064
	ds_read_b128 v[220:223], v244 offset:3072
	ds_read_b128 v[224:227], v244 offset:3088
	s_waitcnt lgkmcnt(0)
	s_waitcnt vmcnt(7)
	v_pk_fma_f32 v[8:9], v[164:165], v[196:197], v[8:9] op_sel_hi:[1,0,1]
	v_pk_fma_f32 v[10:11], v[166:167], v[196:197], v[10:11] op_sel_hi:[1,0,1]
	v_pk_fma_f32 v[12:13], v[164:165], v[204:205], v[12:13] op_sel_hi:[1,0,1]
	v_pk_fma_f32 v[14:15], v[166:167], v[204:205], v[14:15] op_sel_hi:[1,0,1]
	v_pk_fma_f32 v[4:5], v[164:165], v[212:213], v[4:5] op_sel_hi:[1,0,1]
	v_pk_fma_f32 v[6:7], v[166:167], v[212:213], v[6:7] op_sel_hi:[1,0,1]
	v_pk_fma_f32 v[0:1], v[164:165], v[220:221], v[0:1] op_sel_hi:[1,0,1]
	v_pk_fma_f32 v[2:3], v[166:167], v[220:221], v[2:3] op_sel_hi:[1,0,1]
	s_waitcnt vmcnt(6)
	v_pk_fma_f32 v[8:9], v[168:169], v[196:197], v[8:9] op_sel:[0,1,0]
	v_pk_fma_f32 v[10:11], v[170:171], v[196:197], v[10:11] op_sel:[0,1,0]
	v_pk_fma_f32 v[12:13], v[168:169], v[204:205], v[12:13] op_sel:[0,1,0]
	v_pk_fma_f32 v[14:15], v[170:171], v[204:205], v[14:15] op_sel:[0,1,0]
	v_pk_fma_f32 v[4:5], v[168:169], v[212:213], v[4:5] op_sel:[0,1,0]
	v_pk_fma_f32 v[6:7], v[170:171], v[212:213], v[6:7] op_sel:[0,1,0]
	v_pk_fma_f32 v[0:1], v[168:169], v[220:221], v[0:1] op_sel:[0,1,0]
	v_pk_fma_f32 v[2:3], v[170:171], v[220:221], v[2:3] op_sel:[0,1,0]
	s_waitcnt vmcnt(5)
	v_pk_fma_f32 v[8:9], v[172:173], v[198:199], v[8:9] op_sel_hi:[1,0,1]
	v_pk_fma_f32 v[10:11], v[174:175], v[198:199], v[10:11] op_sel_hi:[1,0,1]
	v_pk_fma_f32 v[12:13], v[172:173], v[206:207], v[12:13] op_sel_hi:[1,0,1]
	v_pk_fma_f32 v[14:15], v[174:175], v[206:207], v[14:15] op_sel_hi:[1,0,1]
	v_pk_fma_f32 v[4:5], v[172:173], v[214:215], v[4:5] op_sel_hi:[1,0,1]
	v_pk_fma_f32 v[6:7], v[174:175], v[214:215], v[6:7] op_sel_hi:[1,0,1]
	v_pk_fma_f32 v[0:1], v[172:173], v[222:223], v[0:1] op_sel_hi:[1,0,1]
	v_pk_fma_f32 v[2:3], v[174:175], v[222:223], v[2:3] op_sel_hi:[1,0,1]
	s_waitcnt vmcnt(4)
	v_pk_fma_f32 v[8:9], v[176:177], v[198:199], v[8:9] op_sel:[0,1,0]
	v_pk_fma_f32 v[10:11], v[178:179], v[198:199], v[10:11] op_sel:[0,1,0]
	v_pk_fma_f32 v[12:13], v[176:177], v[206:207], v[12:13] op_sel:[0,1,0]
	v_pk_fma_f32 v[14:15], v[178:179], v[206:207], v[14:15] op_sel:[0,1,0]
	v_pk_fma_f32 v[4:5], v[176:177], v[214:215], v[4:5] op_sel:[0,1,0]
	v_pk_fma_f32 v[6:7], v[178:179], v[214:215], v[6:7] op_sel:[0,1,0]
	v_pk_fma_f32 v[0:1], v[176:177], v[222:223], v[0:1] op_sel:[0,1,0]
	v_pk_fma_f32 v[2:3], v[178:179], v[222:223], v[2:3] op_sel:[0,1,0]
	s_waitcnt vmcnt(3)
	v_pk_fma_f32 v[8:9], v[180:181], v[200:201], v[8:9] op_sel_hi:[1,0,1]
	v_pk_fma_f32 v[10:11], v[182:183], v[200:201], v[10:11] op_sel_hi:[1,0,1]
	v_pk_fma_f32 v[12:13], v[180:181], v[208:209], v[12:13] op_sel_hi:[1,0,1]
	v_pk_fma_f32 v[14:15], v[182:183], v[208:209], v[14:15] op_sel_hi:[1,0,1]
	v_pk_fma_f32 v[4:5], v[180:181], v[216:217], v[4:5] op_sel_hi:[1,0,1]
	v_pk_fma_f32 v[6:7], v[182:183], v[216:217], v[6:7] op_sel_hi:[1,0,1]
	v_pk_fma_f32 v[0:1], v[180:181], v[224:225], v[0:1] op_sel_hi:[1,0,1]
	v_pk_fma_f32 v[2:3], v[182:183], v[224:225], v[2:3] op_sel_hi:[1,0,1]
	s_waitcnt vmcnt(2)
	v_pk_fma_f32 v[8:9], v[184:185], v[200:201], v[8:9] op_sel:[0,1,0]
	v_pk_fma_f32 v[10:11], v[186:187], v[200:201], v[10:11] op_sel:[0,1,0]
	v_pk_fma_f32 v[12:13], v[184:185], v[208:209], v[12:13] op_sel:[0,1,0]
	v_pk_fma_f32 v[14:15], v[186:187], v[208:209], v[14:15] op_sel:[0,1,0]
	v_pk_fma_f32 v[4:5], v[184:185], v[216:217], v[4:5] op_sel:[0,1,0]
	v_pk_fma_f32 v[6:7], v[186:187], v[216:217], v[6:7] op_sel:[0,1,0]
	v_pk_fma_f32 v[0:1], v[184:185], v[224:225], v[0:1] op_sel:[0,1,0]
	v_pk_fma_f32 v[2:3], v[186:187], v[224:225], v[2:3] op_sel:[0,1,0]
	s_waitcnt vmcnt(1)
	v_pk_fma_f32 v[8:9], v[188:189], v[202:203], v[8:9] op_sel_hi:[1,0,1]
	v_pk_fma_f32 v[10:11], v[190:191], v[202:203], v[10:11] op_sel_hi:[1,0,1]
	v_pk_fma_f32 v[12:13], v[188:189], v[210:211], v[12:13] op_sel_hi:[1,0,1]
	v_pk_fma_f32 v[14:15], v[190:191], v[210:211], v[14:15] op_sel_hi:[1,0,1]
	v_pk_fma_f32 v[4:5], v[188:189], v[218:219], v[4:5] op_sel_hi:[1,0,1]
	v_pk_fma_f32 v[6:7], v[190:191], v[218:219], v[6:7] op_sel_hi:[1,0,1]
	v_pk_fma_f32 v[0:1], v[188:189], v[226:227], v[0:1] op_sel_hi:[1,0,1]
	v_pk_fma_f32 v[2:3], v[190:191], v[226:227], v[2:3] op_sel_hi:[1,0,1]
	s_waitcnt vmcnt(0)
	v_pk_fma_f32 v[8:9], v[192:193], v[202:203], v[8:9] op_sel:[0,1,0]
	v_pk_fma_f32 v[10:11], v[194:195], v[202:203], v[10:11] op_sel:[0,1,0]
	v_pk_fma_f32 v[12:13], v[192:193], v[210:211], v[12:13] op_sel:[0,1,0]
	v_pk_fma_f32 v[14:15], v[194:195], v[210:211], v[14:15] op_sel:[0,1,0]
	v_pk_fma_f32 v[4:5], v[192:193], v[218:219], v[4:5] op_sel:[0,1,0]
	v_pk_fma_f32 v[6:7], v[194:195], v[218:219], v[6:7] op_sel:[0,1,0]
	v_pk_fma_f32 v[0:1], v[192:193], v[226:227], v[0:1] op_sel:[0,1,0]
	v_pk_fma_f32 v[2:3], v[194:195], v[226:227], v[2:3] op_sel:[0,1,0]
	s_and_b64 vcc, exec, s[34:35]
	s_cbranch_vccz .LBB0_8
	s_mul_i32 s2, s24, 0x3000
	s_ashr_i32 s3, s2, 31
	v_readlane_b32 s4, v250, 6
	s_lshl_b64 s[2:3], s[2:3], 2
	v_readlane_b32 s12, v250, 14
	v_readlane_b32 s13, v250, 15
	s_add_u32 s2, s12, s2
	s_addc_u32 s3, s13, s3
	s_add_u32 s2, s2, s0
	s_addc_u32 s3, s3, s1
	global_load_dwordx4 v[88:91], v18, s[2:3]
	v_readlane_b32 s5, v250, 7
	v_readlane_b32 s6, v250, 8
	v_readlane_b32 s7, v250, 9
	v_readlane_b32 s8, v250, 10
	v_readlane_b32 s9, v250, 11
	v_readlane_b32 s10, v250, 12
	v_readlane_b32 s11, v250, 13
	v_readlane_b32 s14, v250, 16
	v_readlane_b32 s15, v250, 17
	v_readlane_b32 s16, v250, 18
	v_readlane_b32 s17, v250, 19
	v_readlane_b32 s18, v250, 20
	v_readlane_b32 s19, v250, 21
	s_waitcnt vmcnt(0)
	v_pk_add_f32 v[10:11], v[10:11], v[90:91]
	v_pk_add_f32 v[8:9], v[8:9], v[88:89]
	v_pk_add_f32 v[14:15], v[14:15], v[90:91]
	v_pk_add_f32 v[12:13], v[12:13], v[88:89]
	v_pk_add_f32 v[6:7], v[6:7], v[90:91]
	v_pk_add_f32 v[4:5], v[4:5], v[88:89]
	v_pk_add_f32 v[2:3], v[2:3], v[90:91]
	v_pk_add_f32 v[0:1], v[0:1], v[88:89]
	s_branch .LBB0_8
